# sample_item tail loads hoisted above the gate matvec; in-projection epilogue: row rstd computed once per workgroup instead of per unit
# baseline (speedup 1.0000x reference)
; __device__ __forceinline__ float fexp_(float x) { return __builtin_amdgcn_exp2f(x * 1.44269504089f); }
; __device__ __forceinline__ float sigmoidf_(float x) { return __builtin_amdgcn_rcpf(1.f + fexp_(-x)); }
; __device__ void sample_item(const Params& p, LAS unsigned char* lds, int l, int s, int g) {
;     ...
;     if (tid < 256) {
;         const int j = tid & 63, hl = tid >> 6, h = 4 * g + hl, ch = h * 64 + j;
;         const float* wr = p.in[12] + (size_t)(l * 8 + h) * 4096; const float* wi = p.in[14] + (size_t)(l * 8 + h) * 4096;
;         float r = 0.f, ig = 0.f;
;         for (int i = 0; i < 64; ++i) { const float xv = sxc[hl * 64 + i]; r += xv * wr[i * 64 + j]; ig += xv * wi[i * 64 + j]; }
;         r = sigmoidf_(r + p.in[13][l * 512 + ch]); ig = sigmoidf_(ig + p.in[15][l * 512 + ch]);
;         const float sp = log1pf(fexp_(-p.in[16][l * 512 + ch]));
;         const float la = -8.f * r * sp, a = fexp_(la);
;         const float hn = a * p.in[3][(size_t)(l * NS + s) * 512 + ch] + __builtin_amdgcn_sqrtf(fmaxf(-expm1f(2.f * la), 0.f)) * ig * sxc[tid];
.LBB0_481:
	s_or_b64 exec, exec, s[0:1]
	s_waitcnt lgkmcnt(0)
	s_barrier
	s_and_saveexec_b64 s[0:1], s[40:41]
	s_cbranch_execz .LBB0_446
	v_add_u32_e32 v14, s24, v44
	v_readlane_b32 s2, v254, 47
	v_readlane_b32 s52, v254, 0
	v_readlane_b32 s60, v254, 8
	v_add_u32_e32 v2, s2, v14
	v_ashrrev_i32_e32 v3, 31, v2
	v_lshlrev_b64 v[2:3], 14, v[2:3]
	v_readlane_b32 s61, v254, 9
	v_and_b32_e32 v0, 0x3fffffc0, v114
	v_mov_b32_e32 v39, v1
	v_lshl_add_u64 v[8:9], s[60:61], 0, v[2:3]
	v_readlane_b32 s64, v254, 12
	v_readlane_b32 s65, v254, 13
	v_lshl_add_u32 v15, v0, 2, 0
	v_lshl_add_u64 v[12:13], v[8:9], 0, v[38:39]
	v_lshl_add_u64 v[6:7], s[64:65], 0, v[2:3]
	v_readlane_b32 s2, v254, 52
	v_readlane_b32 s62, v254, 10
	v_readlane_b32 s63, v254, 11
	v_readlane_b32 s53, v254, 1
	v_readlane_b32 s54, v254, 2
	v_readlane_b32 s55, v254, 3
	v_readlane_b32 s56, v254, 4
	v_readlane_b32 s57, v254, 5
	v_readlane_b32 s58, v254, 6
	v_readlane_b32 s59, v254, 7
	v_readlane_b32 s66, v254, 14
	v_readlane_b32 s67, v254, 15
	s_lshl_b64 s[36:37], s[50:51], 11
	v_readlane_b32 s3, v254, 53
	v_lshl_add_u64 v[10:11], v[6:7], 0, v[38:39]
	v_mov_b32_e32 v222, 0x1000
	v_mov_b32_e32 v223, 0
	v_mov_b32_e32 v16, 0
	v_mov_b32_e32 v17, 0
	v_lshl_or_b32 v2, v14, 6, v131
	v_ashrrev_i32_e32 v3, 31, v2
	v_add_u32_e32 v4, s2, v2
	v_ashrrev_i32_e32 v5, 31, v4
	v_lshlrev_b64 v[4:5], 2, v[4:5]
	v_readlane_b32 s54, v254, 16
	v_readlane_b32 s55, v254, 17
	s_add_u32 s56, s10, s36
	s_addc_u32 s57, s11, s37
	v_lshl_add_u64 v[160:161], s[62:63], 0, v[4:5]
	global_load_dword v156, v[160:161], off
	v_lshl_add_u64 v[160:161], s[66:67], 0, v[4:5]
	global_load_dword v157, v[160:161], off
	v_lshl_add_u64 v[160:161], s[54:55], 0, v[4:5]
	global_load_dword v158, v[160:161], off
	v_lshlrev_b64 v[4:5], 2, v[2:3]
	v_lshl_add_u64 v[160:161], s[56:57], 0, v[4:5]
	global_load_dword v159, v[160:161], off
	v_lshlrev_b64 v[4:5], 1, v[2:3]
	v_lshl_add_u64 v[160:161], s[46:47], 0, v[4:5]
	global_load_ushort v168, v[160:161], off offset:1024
	ds_read_b128 v[204:207], v15 offset:9216
	ds_read_b128 v[208:211], v15 offset:9232
	ds_read_b128 v[212:215], v15 offset:9248
	ds_read_b128 v[216:219], v15 offset:9264
	global_load_dword v172, v[12:13], off
	global_load_dword v173, v[10:11], off
	global_load_dword v174, v[12:13], off offset:256
	global_load_dword v175, v[10:11], off offset:256
	global_load_dword v176, v[12:13], off offset:512
	global_load_dword v177, v[10:11], off offset:512
	global_load_dword v178, v[12:13], off offset:768
	global_load_dword v179, v[10:11], off offset:768
	global_load_dword v180, v[12:13], off offset:1024
	global_load_dword v181, v[10:11], off offset:1024
	global_load_dword v182, v[12:13], off offset:1280
	global_load_dword v183, v[10:11], off offset:1280
	global_load_dword v184, v[12:13], off offset:1536
	global_load_dword v185, v[10:11], off offset:1536
	global_load_dword v186, v[12:13], off offset:1792
	global_load_dword v187, v[10:11], off offset:1792
	global_load_dword v188, v[12:13], off offset:2048
	global_load_dword v189, v[10:11], off offset:2048
	global_load_dword v190, v[12:13], off offset:2304
	global_load_dword v191, v[10:11], off offset:2304
	global_load_dword v192, v[12:13], off offset:2560
	global_load_dword v193, v[10:11], off offset:2560
	global_load_dword v194, v[12:13], off offset:2816
	global_load_dword v195, v[10:11], off offset:2816
	global_load_dword v196, v[12:13], off offset:3072
	global_load_dword v197, v[10:11], off offset:3072
	global_load_dword v198, v[12:13], off offset:3328
	global_load_dword v199, v[10:11], off offset:3328
	global_load_dword v200, v[12:13], off offset:3584
	global_load_dword v201, v[10:11], off offset:3584
	global_load_dword v202, v[12:13], off offset:3840
	global_load_dword v203, v[10:11], off offset:3840
	v_lshl_add_u64 v[12:13], v[12:13], 0, v[222:223]
	v_lshl_add_u64 v[10:11], v[10:11], 0, v[222:223]
	s_waitcnt lgkmcnt(0)
	s_waitcnt vmcnt(30)
	v_fmac_f32_e32 v16, v204, v172
	v_fmac_f32_e32 v17, v204, v173
	s_waitcnt vmcnt(28)
	v_fmac_f32_e32 v16, v205, v174
	v_fmac_f32_e32 v17, v205, v175
	s_waitcnt vmcnt(26)
	v_fmac_f32_e32 v16, v206, v176
	v_fmac_f32_e32 v17, v206, v177
	s_waitcnt vmcnt(24)
	v_fmac_f32_e32 v16, v207, v178
	v_fmac_f32_e32 v17, v207, v179
	s_waitcnt vmcnt(22)
	v_fmac_f32_e32 v16, v208, v180
	v_fmac_f32_e32 v17, v208, v181
	s_waitcnt vmcnt(20)
	v_fmac_f32_e32 v16, v209, v182
	v_fmac_f32_e32 v17, v209, v183
	s_waitcnt vmcnt(18)
	v_fmac_f32_e32 v16, v210, v184
	v_fmac_f32_e32 v17, v210, v185
	s_waitcnt vmcnt(16)
	v_fmac_f32_e32 v16, v211, v186
	v_fmac_f32_e32 v17, v211, v187
	s_waitcnt vmcnt(14)
	v_fmac_f32_e32 v16, v212, v188
	v_fmac_f32_e32 v17, v212, v189
	s_waitcnt vmcnt(12)
	v_fmac_f32_e32 v16, v213, v190
	v_fmac_f32_e32 v17, v213, v191
	s_waitcnt vmcnt(10)
	v_fmac_f32_e32 v16, v214, v192
	v_fmac_f32_e32 v17, v214, v193
	s_waitcnt vmcnt(8)
	v_fmac_f32_e32 v16, v215, v194
	v_fmac_f32_e32 v17, v215, v195
	s_waitcnt vmcnt(6)
	v_fmac_f32_e32 v16, v216, v196
	v_fmac_f32_e32 v17, v216, v197
	s_waitcnt vmcnt(4)
	v_fmac_f32_e32 v16, v217, v198
	v_fmac_f32_e32 v17, v217, v199
	s_waitcnt vmcnt(2)
	v_fmac_f32_e32 v16, v218, v200
	v_fmac_f32_e32 v17, v218, v201
	s_waitcnt vmcnt(0)
; __device__ void sample_item(const Params& p, LAS unsigned char* lds, int l, int s, int g) {
;     ...
;         for (int i = 0; i < 64; ++i) { const float xv = sxc[hl * 64 + i]; r += xv * wr[i * 64 + j]; ig += xv * wi[i * 64 + j]; }
	v_fmac_f32_e32 v16, v219, v202
	v_fmac_f32_e32 v17, v219, v203
	ds_read_b128 v[204:207], v15 offset:9280
	ds_read_b128 v[208:211], v15 offset:9296
	ds_read_b128 v[212:215], v15 offset:9312
	ds_read_b128 v[216:219], v15 offset:9328
	global_load_dword v172, v[12:13], off
	global_load_dword v173, v[10:11], off
	global_load_dword v174, v[12:13], off offset:256
	global_load_dword v175, v[10:11], off offset:256
	global_load_dword v176, v[12:13], off offset:512
	global_load_dword v177, v[10:11], off offset:512
	global_load_dword v178, v[12:13], off offset:768
	global_load_dword v179, v[10:11], off offset:768
	global_load_dword v180, v[12:13], off offset:1024
	global_load_dword v181, v[10:11], off offset:1024
	global_load_dword v182, v[12:13], off offset:1280
	global_load_dword v183, v[10:11], off offset:1280
	global_load_dword v184, v[12:13], off offset:1536
	global_load_dword v185, v[10:11], off offset:1536
	global_load_dword v186, v[12:13], off offset:1792
	global_load_dword v187, v[10:11], off offset:1792
	global_load_dword v188, v[12:13], off offset:2048
	global_load_dword v189, v[10:11], off offset:2048
	global_load_dword v190, v[12:13], off offset:2304
	global_load_dword v191, v[10:11], off offset:2304
	global_load_dword v192, v[12:13], off offset:2560
	global_load_dword v193, v[10:11], off offset:2560
	global_load_dword v194, v[12:13], off offset:2816
	global_load_dword v195, v[10:11], off offset:2816
	global_load_dword v196, v[12:13], off offset:3072
	global_load_dword v197, v[10:11], off offset:3072
	global_load_dword v198, v[12:13], off offset:3328
	global_load_dword v199, v[10:11], off offset:3328
	global_load_dword v200, v[12:13], off offset:3584
	global_load_dword v201, v[10:11], off offset:3584
	global_load_dword v202, v[12:13], off offset:3840
	global_load_dword v203, v[10:11], off offset:3840
	v_lshl_add_u64 v[12:13], v[12:13], 0, v[222:223]
	v_lshl_add_u64 v[10:11], v[10:11], 0, v[222:223]
	s_waitcnt lgkmcnt(0)
	s_waitcnt vmcnt(30)
	v_fmac_f32_e32 v16, v204, v172
	v_fmac_f32_e32 v17, v204, v173
	s_waitcnt vmcnt(28)
	v_fmac_f32_e32 v16, v205, v174
	v_fmac_f32_e32 v17, v205, v175
	s_waitcnt vmcnt(26)
	v_fmac_f32_e32 v16, v206, v176
	v_fmac_f32_e32 v17, v206, v177
	s_waitcnt vmcnt(24)
	v_fmac_f32_e32 v16, v207, v178
	v_fmac_f32_e32 v17, v207, v179
	s_waitcnt vmcnt(22)
	v_fmac_f32_e32 v16, v208, v180
	v_fmac_f32_e32 v17, v208, v181
	s_waitcnt vmcnt(20)
	v_fmac_f32_e32 v16, v209, v182
	v_fmac_f32_e32 v17, v209, v183
	s_waitcnt vmcnt(18)
	v_fmac_f32_e32 v16, v210, v184
	v_fmac_f32_e32 v17, v210, v185
	s_waitcnt vmcnt(16)
	v_fmac_f32_e32 v16, v211, v186
	v_fmac_f32_e32 v17, v211, v187
	s_waitcnt vmcnt(14)
	v_fmac_f32_e32 v16, v212, v188
	v_fmac_f32_e32 v17, v212, v189
	s_waitcnt vmcnt(12)
	v_fmac_f32_e32 v16, v213, v190
	v_fmac_f32_e32 v17, v213, v191
	s_waitcnt vmcnt(10)
	v_fmac_f32_e32 v16, v214, v192
	v_fmac_f32_e32 v17, v214, v193
	s_waitcnt vmcnt(8)
	v_fmac_f32_e32 v16, v215, v194
	v_fmac_f32_e32 v17, v215, v195
	s_waitcnt vmcnt(6)
	v_fmac_f32_e32 v16, v216, v196
	v_fmac_f32_e32 v17, v216, v197
	s_waitcnt vmcnt(4)
	v_fmac_f32_e32 v16, v217, v198
	v_fmac_f32_e32 v17, v217, v199
	s_waitcnt vmcnt(2)
	v_fmac_f32_e32 v16, v218, v200
	v_fmac_f32_e32 v17, v218, v201
	s_waitcnt vmcnt(0)
	v_fmac_f32_e32 v16, v219, v202
	v_fmac_f32_e32 v17, v219, v203
	ds_read_b128 v[204:207], v15 offset:9344
	ds_read_b128 v[208:211], v15 offset:9360
	ds_read_b128 v[212:215], v15 offset:9376
	ds_read_b128 v[216:219], v15 offset:9392
	global_load_dword v172, v[12:13], off
	global_load_dword v173, v[10:11], off
	global_load_dword v174, v[12:13], off offset:256
	global_load_dword v175, v[10:11], off offset:256
	global_load_dword v176, v[12:13], off offset:512
	global_load_dword v177, v[10:11], off offset:512
	global_load_dword v178, v[12:13], off offset:768
	global_load_dword v179, v[10:11], off offset:768
	global_load_dword v180, v[12:13], off offset:1024
	global_load_dword v181, v[10:11], off offset:1024
	global_load_dword v182, v[12:13], off offset:1280
	global_load_dword v183, v[10:11], off offset:1280
	global_load_dword v184, v[12:13], off offset:1536
	global_load_dword v185, v[10:11], off offset:1536
	global_load_dword v186, v[12:13], off offset:1792
	global_load_dword v187, v[10:11], off offset:1792
	global_load_dword v188, v[12:13], off offset:2048
	global_load_dword v189, v[10:11], off offset:2048
	global_load_dword v190, v[12:13], off offset:2304
	global_load_dword v191, v[10:11], off offset:2304
	global_load_dword v192, v[12:13], off offset:2560
	global_load_dword v193, v[10:11], off offset:2560
	global_load_dword v194, v[12:13], off offset:2816
	global_load_dword v195, v[10:11], off offset:2816
	global_load_dword v196, v[12:13], off offset:3072
	global_load_dword v197, v[10:11], off offset:3072
	global_load_dword v198, v[12:13], off offset:3328
	global_load_dword v199, v[10:11], off offset:3328
	global_load_dword v200, v[12:13], off offset:3584
	global_load_dword v201, v[10:11], off offset:3584
	global_load_dword v202, v[12:13], off offset:3840
	global_load_dword v203, v[10:11], off offset:3840
	v_lshl_add_u64 v[12:13], v[12:13], 0, v[222:223]
	v_lshl_add_u64 v[10:11], v[10:11], 0, v[222:223]
	s_waitcnt lgkmcnt(0)
	s_waitcnt vmcnt(30)
	v_fmac_f32_e32 v16, v204, v172
	v_fmac_f32_e32 v17, v204, v173
	s_waitcnt vmcnt(28)
	v_fmac_f32_e32 v16, v205, v174
	v_fmac_f32_e32 v17, v205, v175
	s_waitcnt vmcnt(26)
	v_fmac_f32_e32 v16, v206, v176
	v_fmac_f32_e32 v17, v206, v177
	s_waitcnt vmcnt(24)
	v_fmac_f32_e32 v16, v207, v178
	v_fmac_f32_e32 v17, v207, v179
	s_waitcnt vmcnt(22)
	v_fmac_f32_e32 v16, v208, v180
	v_fmac_f32_e32 v17, v208, v181
	s_waitcnt vmcnt(20)
; __device__ __forceinline__ float fexp_(float x) { return __builtin_amdgcn_exp2f(x * 1.44269504089f); }
; __device__ __forceinline__ float sigmoidf_(float x) { return __builtin_amdgcn_rcpf(1.f + fexp_(-x)); }
; __device__ void sample_item(const Params& p, LAS unsigned char* lds, int l, int s, int g) {
;     ...
;         for (int i = 0; i < 64; ++i) { const float xv = sxc[hl * 64 + i]; r += xv * wr[i * 64 + j]; ig += xv * wi[i * 64 + j]; }
;         r = sigmoidf_(r + p.in[13][l * 512 + ch]); ig = sigmoidf_(ig + p.in[15][l * 512 + ch]);
;         const float sp = log1pf(fexp_(-p.in[16][l * 512 + ch]));
;         const float la = -8.f * r * sp, a = fexp_(la);
;         const float hn = a * p.in[3][(size_t)(l * NS + s) * 512 + ch] + __builtin_amdgcn_sqrtf(fmaxf(-expm1f(2.f * la), 0.f)) * ig * sxc[tid];
	v_fmac_f32_e32 v16, v209, v182
	v_fmac_f32_e32 v17, v209, v183
	s_waitcnt vmcnt(18)
	v_fmac_f32_e32 v16, v210, v184
	v_fmac_f32_e32 v17, v210, v185
	s_waitcnt vmcnt(16)
	v_fmac_f32_e32 v16, v211, v186
	v_fmac_f32_e32 v17, v211, v187
	s_waitcnt vmcnt(14)
	v_fmac_f32_e32 v16, v212, v188
	v_fmac_f32_e32 v17, v212, v189
	s_waitcnt vmcnt(12)
	v_fmac_f32_e32 v16, v213, v190
	v_fmac_f32_e32 v17, v213, v191
	s_waitcnt vmcnt(10)
	v_fmac_f32_e32 v16, v214, v192
	v_fmac_f32_e32 v17, v214, v193
	s_waitcnt vmcnt(8)
	v_fmac_f32_e32 v16, v215, v194
	v_fmac_f32_e32 v17, v215, v195
	s_waitcnt vmcnt(6)
	v_fmac_f32_e32 v16, v216, v196
	v_fmac_f32_e32 v17, v216, v197
	s_waitcnt vmcnt(4)
	v_fmac_f32_e32 v16, v217, v198
	v_fmac_f32_e32 v17, v217, v199
	s_waitcnt vmcnt(2)
	v_fmac_f32_e32 v16, v218, v200
	v_fmac_f32_e32 v17, v218, v201
	s_waitcnt vmcnt(0)
	v_fmac_f32_e32 v16, v219, v202
	v_fmac_f32_e32 v17, v219, v203
	ds_read_b128 v[204:207], v15 offset:9408
	ds_read_b128 v[208:211], v15 offset:9424
	ds_read_b128 v[212:215], v15 offset:9440
	ds_read_b128 v[216:219], v15 offset:9456
	global_load_dword v172, v[12:13], off
	global_load_dword v173, v[10:11], off
	global_load_dword v174, v[12:13], off offset:256
	global_load_dword v175, v[10:11], off offset:256
	global_load_dword v176, v[12:13], off offset:512
	global_load_dword v177, v[10:11], off offset:512
	global_load_dword v178, v[12:13], off offset:768
	global_load_dword v179, v[10:11], off offset:768
	global_load_dword v180, v[12:13], off offset:1024
	global_load_dword v181, v[10:11], off offset:1024
	global_load_dword v182, v[12:13], off offset:1280
	global_load_dword v183, v[10:11], off offset:1280
	global_load_dword v184, v[12:13], off offset:1536
	global_load_dword v185, v[10:11], off offset:1536
	global_load_dword v186, v[12:13], off offset:1792
	global_load_dword v187, v[10:11], off offset:1792
	global_load_dword v188, v[12:13], off offset:2048
	global_load_dword v189, v[10:11], off offset:2048
	global_load_dword v190, v[12:13], off offset:2304
	global_load_dword v191, v[10:11], off offset:2304
	global_load_dword v192, v[12:13], off offset:2560
	global_load_dword v193, v[10:11], off offset:2560
	global_load_dword v194, v[12:13], off offset:2816
	global_load_dword v195, v[10:11], off offset:2816
	global_load_dword v196, v[12:13], off offset:3072
	global_load_dword v197, v[10:11], off offset:3072
	global_load_dword v198, v[12:13], off offset:3328
	global_load_dword v199, v[10:11], off offset:3328
	global_load_dword v200, v[12:13], off offset:3584
	global_load_dword v201, v[10:11], off offset:3584
	global_load_dword v202, v[12:13], off offset:3840
	global_load_dword v203, v[10:11], off offset:3840
	s_waitcnt lgkmcnt(0)
	s_waitcnt vmcnt(30)
	v_fmac_f32_e32 v16, v204, v172
	v_fmac_f32_e32 v17, v204, v173
	s_waitcnt vmcnt(28)
	v_fmac_f32_e32 v16, v205, v174
	v_fmac_f32_e32 v17, v205, v175
	s_waitcnt vmcnt(26)
	v_fmac_f32_e32 v16, v206, v176
	v_fmac_f32_e32 v17, v206, v177
	s_waitcnt vmcnt(24)
	v_fmac_f32_e32 v16, v207, v178
	v_fmac_f32_e32 v17, v207, v179
	s_waitcnt vmcnt(22)
	v_fmac_f32_e32 v16, v208, v180
	v_fmac_f32_e32 v17, v208, v181
	s_waitcnt vmcnt(20)
	v_fmac_f32_e32 v16, v209, v182
	v_fmac_f32_e32 v17, v209, v183
	s_waitcnt vmcnt(18)
	v_fmac_f32_e32 v16, v210, v184
	v_fmac_f32_e32 v17, v210, v185
	s_waitcnt vmcnt(16)
	v_fmac_f32_e32 v16, v211, v186
	v_fmac_f32_e32 v17, v211, v187
	s_waitcnt vmcnt(14)
	v_fmac_f32_e32 v16, v212, v188
	v_fmac_f32_e32 v17, v212, v189
	s_waitcnt vmcnt(12)
	v_fmac_f32_e32 v16, v213, v190
	v_fmac_f32_e32 v17, v213, v191
	s_waitcnt vmcnt(10)
	v_fmac_f32_e32 v16, v214, v192
	v_fmac_f32_e32 v17, v214, v193
	s_waitcnt vmcnt(8)
	v_fmac_f32_e32 v16, v215, v194
	v_fmac_f32_e32 v17, v215, v195
	s_waitcnt vmcnt(6)
	v_fmac_f32_e32 v16, v216, v196
	v_fmac_f32_e32 v17, v216, v197
	s_waitcnt vmcnt(4)
	v_fmac_f32_e32 v16, v217, v198
	v_fmac_f32_e32 v17, v217, v199
	s_waitcnt vmcnt(2)
	v_fmac_f32_e32 v16, v218, v200
	v_fmac_f32_e32 v17, v218, v201
	s_waitcnt vmcnt(0)
	v_fmac_f32_e32 v16, v219, v202
	v_fmac_f32_e32 v17, v219, v203
	v_lshl_or_b32 v2, v14, 6, v131
	v_add_u32_e32 v4, s2, v2
	v_ashrrev_i32_e32 v5, 31, v4
	v_lshlrev_b64 v[4:5], 2, v[4:5]
	v_mov_b32_e32 v3, v16
	v_mov_b32_e32 v0, v17
	s_mov_b32 s2, 0x3f2aaaab
	v_add_f32_e32 v3, v3, v156
	v_readlane_b32 s52, v254, 16
	v_readlane_b32 s53, v254, 17
	v_mul_f32_e32 v3, 0xbfb8aa3b, v3
	v_mov_b32_e32 v4, v158
	v_exp_f32_e32 v3, v3
	v_readlane_b32 s54, v254, 18
	v_readlane_b32 s55, v254, 19
	v_readlane_b32 s56, v254, 20
	v_add_f32_e32 v3, 1.0, v3
	v_rcp_f32_e32 v3, v3
	v_readlane_b32 s57, v254, 21
	v_readlane_b32 s58, v254, 22
	v_readlane_b32 s59, v254, 23
	v_mul_f32_e32 v3, 0xc1000000, v3
	v_readlane_b32 s60, v254, 24
	v_readlane_b32 s61, v254, 25
	v_readlane_b32 s62, v254, 26
	v_readlane_b32 s63, v254, 27
	v_readlane_b32 s64, v254, 28
	v_readlane_b32 s65, v254, 29
	v_readlane_b32 s66, v254, 30
	v_readlane_b32 s67, v254, 31
	v_readlane_b32 s52, v251, 6
	v_readlane_b32 s66, v251, 20
	v_readlane_b32 s67, v251, 21
	v_readlane_b32 s53, v251, 7
	v_readlane_b32 s54, v251, 8
	v_readlane_b32 s55, v251, 9
	v_readlane_b32 s56, v251, 10
	v_readlane_b32 s57, v251, 11
	v_readlane_b32 s58, v251, 12
	v_readlane_b32 s59, v251, 13
	v_readlane_b32 s60, v251, 14
	v_readlane_b32 s61, v251, 15
	v_readlane_b32 s62, v251, 16
	v_readlane_b32 s63, v251, 17
	v_readlane_b32 s64, v251, 18
	v_readlane_b32 s65, v251, 19
	v_add_f32_e32 v0, v0, v157
	v_mul_f32_e32 v0, 0xbfb8aa3b, v0
	v_exp_f32_e32 v0, v0
	v_mul_f32_e32 v4, 0xbfb8aa3b, v4
	v_exp_f32_e32 v18, v4
	v_add_f32_e32 v0, 1.0, v0
	v_rcp_f32_e32 v0, v0
	v_add_f32_e32 v6, 1.0, v18
	v_add_f32_e32 v4, -1.0, v6
; __device__ __forceinline__ float bf2f(bf16_t v) { return __uint_as_float(((unsigned)v) << 16); }
; __device__ __forceinline__ bf16_t f2bf(float f) { return (bf16_t)(pk2(f, 0.f) & 0xffffu); }
; __device__ __forceinline__ float fexp_(float x) { return __builtin_amdgcn_exp2f(x * 1.44269504089f); }
; __device__ __forceinline__ float geluf_(float x) { const float z = x * __builtin_fmaf(x * x, 0.1029432397f, 2.302208198f); const float r = __builtin_amdgcn_rcpf(1.f + __builtin_amdgcn_exp2f(z)); return __builtin_fmaf(-x, r, x); }
; __device__ void sample_item(const Params& p, LAS unsigned char* lds, int l, int s, int g) {
;     ...
;         const float sp = log1pf(fexp_(-p.in[16][l * 512 + ch]));
;         const float la = -8.f * r * sp, a = fexp_(la);
;         const float hn = a * p.in[3][(size_t)(l * NS + s) * 512 + ch] + __builtin_amdgcn_sqrtf(fmaxf(-expm1f(2.f * la), 0.f)) * ig * sxc[tid];
;         p.out[O_LHS + (size_t)(l * NS + s) * 512 + ch] = hn;
;         mix[t * DMIX + ch] = f2bf(hn * geluf_(bf2f(prow[PC_LG + ch])));
	v_sub_f32_e32 v5, v4, v6
	v_add_f32_e32 v5, 1.0, v5
	v_sub_f32_e32 v4, v18, v4
	v_add_f32_e32 v7, v4, v5
	v_frexp_mant_f32_e32 v4, v6
	v_cmp_gt_f32_e32 vcc, s2, v4
	v_cvt_f64_f32_e32 v[4:5], v6
	v_frexp_exp_i32_f64_e32 v4, v[4:5]
	v_subbrev_co_u32_e32 v12, vcc, 0, v4, vcc
	v_sub_u32_e32 v4, 0, v12
	v_ldexp_f32 v5, v6, v4
	v_add_f32_e32 v6, -1.0, v5
	v_add_f32_e32 v8, 1.0, v5
	v_ldexp_f32 v4, v7, v4
	v_add_f32_e32 v7, 1.0, v6
	v_add_f32_e32 v9, -1.0, v8
	v_sub_f32_e32 v7, v5, v7
	v_sub_f32_e32 v5, v5, v9
	v_add_f32_e32 v7, v4, v7
	v_add_f32_e32 v4, v4, v5
	v_add_f32_e32 v13, v8, v4
	v_rcp_f32_e32 v15, v13
	v_sub_f32_e32 v5, v13, v8
	v_sub_f32_e32 v14, v4, v5
	v_add_f32_e32 v5, v6, v7
	v_mul_f32_e32 v17, v5, v15
	v_sub_f32_e32 v4, v5, v6
	v_mul_f32_e32 v6, v13, v17
	v_fma_f32 v8, v17, v13, -v6
	v_fmac_f32_e32 v8, v17, v14
	v_sub_f32_e32 v16, v7, v4
	v_add_f32_e32 v4, v6, v8
	v_sub_f32_e32 v7, v5, v4
	v_pk_add_f32 v[10:11], v[4:5], v[6:7] neg_lo:[0,1] neg_hi:[0,1]
	v_mov_b32_e32 v9, v4
	v_pk_add_f32 v[4:5], v[10:11], v[8:9] neg_lo:[0,1] neg_hi:[0,1]
	s_mov_b32 s2, 0x3f317218
	v_add_f32_e32 v5, v16, v5
	v_add_f32_e32 v4, v4, v5
	v_add_f32_e32 v5, v7, v4
	v_mul_f32_e32 v16, v15, v5
	v_mul_f32_e32 v6, v13, v16
	v_fma_f32 v8, v16, v13, -v6
	v_fmac_f32_e32 v8, v16, v14
	v_sub_f32_e32 v7, v7, v5
	v_add_f32_e32 v13, v4, v7
	v_add_f32_e32 v4, v6, v8
	v_sub_f32_e32 v7, v5, v4
	v_pk_add_f32 v[10:11], v[4:5], v[6:7] neg_lo:[0,1] neg_hi:[0,1]
	v_mov_b32_e32 v9, v4
	v_pk_add_f32 v[4:5], v[10:11], v[8:9] neg_lo:[0,1] neg_hi:[0,1]
	s_nop 0
	v_add_f32_e32 v5, v13, v5
	v_add_f32_e32 v4, v4, v5
	v_add_f32_e32 v5, v17, v16
	v_add_f32_e32 v4, v7, v4
	v_sub_f32_e32 v6, v5, v17
	v_mul_f32_e32 v4, v15, v4
	v_sub_f32_e32 v6, v16, v6
	v_add_f32_e32 v6, v6, v4
	v_add_f32_e32 v8, v5, v6
	v_mul_f32_e32 v9, v8, v8
	v_fmamk_f32 v4, v9, 0x3e9b6dac, v225
	v_fmaak_f32 v171, v9, v4, 0x3f2aaada
	v_cvt_f32_i32_e32 v4, v12
	v_sub_f32_e32 v5, v8, v5
	v_sub_f32_e32 v5, v6, v5
	v_ldexp_f32 v10, v5, 1
	v_mul_f32_e32 v5, v8, v9
	v_ldexp_f32 v7, v8, 1
	v_pk_mul_f32 v[8:9], v[4:5], v[170:171]
	s_nop 0
	v_fma_f32 v6, v4, s2, -v8
	v_fmac_f32_e32 v6, 0xb102e308, v4
	v_pk_add_f32 v[4:5], v[8:9], v[6:7]
	s_mov_b32 s2, 0x7f800000
	v_sub_f32_e32 v7, v5, v7
	v_sub_f32_e32 v7, v9, v7
	v_add_f32_e32 v11, v10, v7
	v_mov_b32_e32 v10, v8
	v_pk_add_f32 v[8:9], v[4:5], v[8:9] neg_lo:[0,1] neg_hi:[0,1]
	v_pk_add_f32 v[12:13], v[4:5], v[10:11]
	v_mov_b32_e32 v7, v4
	v_mov_b32_e32 v9, v13
	v_pk_add_f32 v[14:15], v[6:7], v[8:9] neg_lo:[0,1] neg_hi:[0,1]
	v_pk_add_f32 v[6:7], v[6:7], v[8:9]
	v_mov_b32_e32 v10, v11
	v_pk_add_f32 v[8:9], v[6:7], v[4:5] op_sel:[1,0] op_sel_hi:[0,1] neg_lo:[0,1] neg_hi:[0,1]
	v_pk_add_f32 v[16:17], v[12:13], v[8:9] op_sel_hi:[1,0] neg_lo:[0,1] neg_hi:[0,1]
	v_mov_b32_e32 v12, v13
	v_mov_b32_e32 v13, v7
	v_pk_mov_b32 v[8:9], v[4:5], v[8:9] op_sel:[1,0]
	v_mov_b32_e32 v11, v4
	v_pk_add_f32 v[8:9], v[12:13], v[8:9] neg_lo:[0,1] neg_hi:[0,1]
	v_mov_b32_e32 v16, v14
	v_pk_add_f32 v[4:5], v[10:11], v[8:9] neg_lo:[0,1] neg_hi:[0,1]
	v_mov_b32_e32 v15, v7
	v_pk_add_f32 v[8:9], v[16:17], v[4:5]
	v_cmp_neq_f32_e32 vcc, s2, v18
	v_pk_add_f32 v[10:11], v[8:9], v[8:9] op_sel:[0,1] op_sel_hi:[1,0]
	s_mov_b32 s2, 0x33800000
	v_pk_add_f32 v[6:7], v[6:7], v[10:11] op_sel:[1,0] op_sel_hi:[0,1]
	v_mov_b32_e32 v9, v6
	v_pk_add_f32 v[12:13], v[8:9], v[14:15] neg_lo:[0,1] neg_hi:[0,1]
	v_mov_b32_e32 v5, v10
	v_sub_f32_e32 v7, v8, v12
	v_pk_add_f32 v[4:5], v[4:5], v[12:13] neg_lo:[0,1] neg_hi:[0,1]
	v_sub_f32_e32 v7, v14, v7
	v_add_f32_e32 v4, v4, v7
	v_add_f32_e32 v4, v4, v5
	v_add_f32_e32 v4, v6, v4
	v_cndmask_b32_e32 v4, v234, v4, vcc
	v_cmp_ngt_f32_e32 vcc, -1.0, v18
	v_mov_b32_e32 v11, 0x3ab69700
	s_nop 0
	v_cndmask_b32_e32 v4, v232, v4, vcc
	v_cmp_neq_f32_e32 vcc, -1.0, v18
	s_nop 1
	v_cndmask_b32_e32 v4, v233, v4, vcc
	v_cmp_lt_f32_e64 vcc, |v18|, s2
	s_add_u32 s2, s10, s36
	s_addc_u32 s3, s11, s37
	v_cndmask_b32_e32 v4, v4, v18, vcc
	v_mul_f32_e32 v7, v3, v4
	v_mul_f32_e32 v3, 0x3fb8aa3b, v7
	v_exp_f32_e32 v6, v3
	v_ashrrev_i32_e32 v3, 31, v2
	v_lshlrev_b64 v[4:5], 2, v[2:3]
	v_mov_b32_e32 v8, v159
	v_add_f32_e32 v7, v7, v7
	v_mul_f32_e32 v9, 0x3fb8aa3b, v7
	v_rndne_f32_e32 v9, v9
	v_fmamk_f32 v10, v9, 0xbf317218, v7
	v_fmac_f32_e32 v10, 0x3102e308, v9
	s_mov_b32 s2, 0x43000000
	v_fmamk_f32 v11, v10, 0x395133b1, v11
	v_cmp_eq_f32_e32 vcc, s2, v9
	v_cvt_i32_f32_e32 v9, v9
	v_fmaak_f32 v11, v10, v11, 0x3c0887f9
	v_fmaak_f32 v11, v10, v11, 0x3d2aaa81
	v_fmaak_f32 v11, v10, v11, 0x3e2aaaab
	v_fma_f32 v11, v10, v11, 0.5
	v_ldexp_f32 v9, 1.0, v9
	v_mul_f32_e32 v11, v10, v11
	v_cndmask_b32_e32 v9, v9, v238, vcc
	v_fmac_f32_e32 v10, v10, v11
	v_add_f32_e32 v11, -1.0, v9
	v_fmac_f32_e32 v11, v9, v10
	v_add_f32_e32 v9, v11, v11
	v_cndmask_b32_e32 v9, v11, v9, vcc
	s_mov_b32 s2, 0x42b17217
	v_max_f32_e64 v9, -v9, 0
	v_cmp_nlt_f32_e32 vcc, s2, v7
	s_mov_b32 s2, 0xc1880000
	v_lshlrev_b64 v[2:3], 1, v[2:3]
	v_cndmask_b32_e32 v9, 0, v9, vcc
	v_cmp_ngt_f32_e32 vcc, s2, v7
	s_add_u32 s2, s66, s36
	s_addc_u32 s3, s67, s37
	v_cndmask_b32_e32 v7, 1.0, v9, vcc
	v_sqrt_f32_e32 v7, v7
	ds_read_b32 v9, v130 offset:9216
	v_lshl_add_u64 v[4:5], s[2:3], 0, v[4:5]
	s_mov_b32 s2, 0x43c0000
	v_mul_f32_e32 v7, v0, v7
	v_add_co_u32_e32 v4, vcc, s2, v4
	s_waitcnt lgkmcnt(0)
	v_pk_mul_f32 v[6:7], v[8:9], v[6:7]
	s_nop 0
	v_add_f32_e32 v0, v6, v7
	v_addc_co_u32_e32 v5, vcc, 0, v5, vcc
	global_store_dword v[4:5], v0, off
	v_lshl_add_u64 v[2:3], s[48:49], 0, v[2:3]
	v_lshlrev_b32_e32 v4, 16, v168
	v_mul_f32_e32 v5, v4, v4
	v_fmamk_f32 v5, v5, 0x3dd2d3e8, v224
	v_mul_f32_e32 v5, v5, v4
	v_exp_f32_e32 v5, v5
	s_nop 0
	v_add_f32_e32 v5, 1.0, v5
	v_rcp_f32_e32 v5, v5
	s_nop 0
	v_fma_f32 v4, -v4, v5, v4
	v_mul_f32_e32 v0, v4, v0
	v_cvt_pk_bf16_f32 v0, v0, v1
	global_store_short v[2:3], v0, off
	s_branch .LBB0_446

; __device__ __forceinline__ float rstd_fix(u64 v) { return rsqrtf((float)v * (1.f / (1048576.f * 1024.f)) + 1e-6f); }
; #define PG8_STAGE(bufoff, gbase, voff) do { _Pragma("unroll") for (int _i = 0; _i < 2; ++_i) \
;         __builtin_amdgcn_global_load_lds((const unsigned*)((const char*)(gbase) + (voff)[_i]), (LAS unsigned*)(lds + (bufoff) + ldsw + _i * 8192), 16, 0, 0); } while (0)
; #define PG8_WAIT_V(n) asm volatile("s_waitcnt vmcnt(" #n ")" ::: "memory")
; #define PG8_BAR __builtin_amdgcn_s_barrier()
; template <class Epi>
; __device__ __forceinline__ void gemm_phase(LAS unsigned char* lds, const Gemm g, const StaticOrder& S, const Epi& E) {
;     ...
;     const char* cA = (const char*)g.A + (size_t)cur.pm * tstep; const char* cB = (const char*)g.Bt + (size_t)cur.pn * tstep;
;     PG8_STAGE(PG8_SB(0, 0), cB, voffB); PG8_STAGE(PG8_SA(0, 0), cA, voffA); PG8_STAGE(PG8_SB(0, 1), cB + hstep, voffB); PG8_STAGE(PG8_SA(0, 1), cA + hstep, voffA);
;     if (wr == 1) PG8_BAR;
;     PG8_WAIT_V(4); PG8_BAR;
;     PG8_STAGE(PG8_SB(1, 0), cB + kstep, voffB); PG8_STAGE(PG8_SA(1, 0), cA + kstep, voffA); PG8_STAGE(PG8_SB(1, 1), cB + hstep + kstep, voffB);
;     PG8_WAIT_V(6); PG8_BAR;
;     __device__ __forceinline__ void operator()(const f32x4 (&acc)[2][2][4][2], const Unit& u, int wr, int wc, int fr, int fq) const {
;         const int row0 = u.pm * BM + wr * 64 + fr, col0 = u.pn * BM + wc * 32 + 8 * fq;
;         u64 rv[2][4];
; #pragma unroll
;         for (int ai = 0; ai < 2; ++ai)
; #pragma unroll
;             for (int m = 0; m < 4; ++m) rv[ai][m] = rss[row0 + ai * HALF + m * 16];
; #pragma unroll
;         for (int ai = 0; ai < 2; ++ai)
; #pragma unroll
;             for (int m = 0; m < 4; ++m) { const int row = row0 + ai * HALF + m * 16; bf16_t* rowp = O + (size_t)row * ldc + col0;
;                 const float rs = rstd_fix(rv[ai][m]);
.LBB0_497:
	v_lshl_add_u64 v[10:11], s[48:49], 0, v[0:1]
	v_mov_b32_e32 v131, v1
	v_readlane_b32 s46, v252, 53
	s_lshl_b32 s1, s1, 5
	v_lshl_add_u64 v[12:13], s[48:49], 0, v[130:131]
	v_mov_b32_e32 v135, v1
	v_readlane_b32 s47, v252, 54
	s_and_b32 s1, s1, 0x60
	s_add_i32 m0, s24, 0x18000
	v_lshl_add_u64 v[10:11], v[10:11], 0, s[28:29]
	v_lshl_add_u64 v[14:15], s[46:47], 0, v[134:135]
	v_mov_b32_e32 v133, v1
	s_lshl_b32 s40, s0, 13
	s_lshl_b32 s41, s1, 7
	s_waitcnt vmcnt(4)
	s_barrier
	global_load_lds_dwordx4 v[10:11], off
	v_lshl_add_u64 v[10:11], v[12:13], 0, s[28:29]
	s_add_i32 m0, s24, 0x1a000
	s_add_i32 s53, s24, 0x8000
	s_add_i32 s54, s24, 0xa000
	v_lshl_add_u64 v[16:17], s[46:47], 0, v[132:133]
	global_load_lds_dwordx4 v[10:11], off
	v_lshl_add_u64 v[10:11], v[14:15], 0, s[28:29]
	s_mov_b32 m0, s53
	s_add_u32 s38, s48, 0x40080
	global_load_lds_dwordx4 v[10:11], off
	v_lshl_add_u64 v[10:11], v[16:17], 0, s[28:29]
	s_mov_b32 m0, s54
	s_addc_u32 s39, s49, 0
	global_load_lds_dwordx4 v[10:11], off
	s_add_i32 m0, s24, 0x1c000
	v_lshl_add_u64 v[10:11], s[38:39], 0, v[0:1]
	global_load_lds_dwordx4 v[10:11], off
	v_lshl_add_u64 v[10:11], s[38:39], 0, v[130:131]
	s_add_i32 m0, s24, 0x1e000
	v_and_b32_e32 v9, 15, v2
	global_load_lds_dwordx4 v[10:11], off
	v_lshrrev_b32_e32 v10, 1, v2
	v_and_b32_e32 v10, 24, v10
	v_lshlrev_b32_e32 v11, 1, v10
	v_lshlrev_b32_e32 v2, 2, v2
	v_lshl_or_b32 v168, s0, 6, v9
	v_lshl_or_b32 v9, v9, 6, v11
	v_and_b32_e32 v2, 32, v2
	v_bitop3_b32 v11, v9, s40, v2 bitop3:0xde
	v_bitop3_b32 v171, v9, s41, v2 bitop3:0xde
	v_lshlrev_b32_e32 v2, 14, v7
	v_and_b32_e32 v2, 0xffff8000, v2
	v_lshl_add_u32 v2, v6, 11, v2
	v_and_b32_e32 v6, 1, v7
	v_lshl_or_b32 v2, v6, 6, v2
	v_lshl_add_u32 v136, v8, 1, v2
	v_lshlrev_b32_e32 v2, 14, v3
	v_and_b32_e32 v2, 0xffff8000, v2
	s_waitcnt vmcnt(6)
	v_lshl_add_u32 v2, v4, 11, v2
	v_and_b32_e32 v3, 1, v3
	v_or_b32_e32 v178, s1, v10
	v_lshl_or_b32 v2, v3, 6, v2
	v_readlane_b32 s0, v252, 49
	v_mov_b32_e32 v137, v1
	v_lshl_add_u32 v138, v5, 1, v2
	v_mov_b32_e32 v139, v1
	s_mov_b32 s55, 0
	v_add_u32_e32 v179, 0, v11
	v_readlane_b32 s56, v252, 46
	s_mov_b32 s57, s0
	s_barrier
	v_readlane_b32 s1, v252, 50
	v_lshl_add_u32 v142, s57, 8, v168
	v_ashrrev_i32_e32 v143, 31, v142
	v_lshl_add_u64 v[140:141], v[142:143], 3, s[36:37]
	global_load_dwordx2 v[144:145], v[140:141], off
	global_load_dwordx2 v[146:147], v[140:141], off offset:128
	global_load_dwordx2 v[148:149], v[140:141], off offset:256
	global_load_dwordx2 v[150:151], v[140:141], off offset:384
	global_load_dwordx2 v[152:153], v[140:141], off offset:1024
	global_load_dwordx2 v[154:155], v[140:141], off offset:1152
	global_load_dwordx2 v[156:157], v[140:141], off offset:1280
	global_load_dwordx2 v[158:159], v[140:141], off offset:1408
	s_waitcnt vmcnt(0)
	v_ffbh_u32_e32 v160, v145
	v_min_u32_e32 v160, 32, v160
	v_lshlrev_b64 v[144:145], v160, v[144:145]
	v_min_u32_e32 v144, 1, v144
	v_or_b32_e32 v144, v145, v144
	v_cvt_f32_u32_e32 v144, v144
	v_sub_u32_e32 v145, 32, v160
	v_ldexp_f32 v144, v144, v145
	v_fmamk_f32 v144, v144, 0x30800000, v162
	v_cmp_gt_f32_e32 vcc, s95, v144
	v_mul_f32_e32 v145, 0x4b800000, v144
	s_nop 1
	v_cndmask_b32_e32 v144, v144, v145, vcc
	v_rsq_f32_e32 v144, v144
	s_nop 0
	v_mul_f32_e32 v145, 0x45800000, v144
	v_cndmask_b32_e32 v236, v144, v145, vcc
	v_ffbh_u32_e32 v160, v147
	v_min_u32_e32 v160, 32, v160
	v_lshlrev_b64 v[146:147], v160, v[146:147]
	v_min_u32_e32 v146, 1, v146
	v_or_b32_e32 v146, v147, v146
	v_cvt_f32_u32_e32 v146, v146
	v_sub_u32_e32 v147, 32, v160
	v_ldexp_f32 v146, v146, v147
	v_fmamk_f32 v146, v146, 0x30800000, v162
	v_cmp_gt_f32_e32 vcc, s95, v146
	v_mul_f32_e32 v147, 0x4b800000, v146
	s_nop 1
	v_cndmask_b32_e32 v146, v146, v147, vcc
	v_rsq_f32_e32 v146, v146
	s_nop 0
	v_mul_f32_e32 v147, 0x45800000, v146
	v_cndmask_b32_e32 v237, v146, v147, vcc
	v_ffbh_u32_e32 v160, v149
	v_min_u32_e32 v160, 32, v160
	v_lshlrev_b64 v[148:149], v160, v[148:149]
	v_min_u32_e32 v148, 1, v148
	v_or_b32_e32 v148, v149, v148
	v_cvt_f32_u32_e32 v148, v148
	v_sub_u32_e32 v149, 32, v160
	v_ldexp_f32 v148, v148, v149
	v_fmamk_f32 v148, v148, 0x30800000, v162
	v_cmp_gt_f32_e32 vcc, s95, v148
	v_mul_f32_e32 v149, 0x4b800000, v148
	s_nop 1
	v_cndmask_b32_e32 v148, v148, v149, vcc
	v_rsq_f32_e32 v148, v148
	s_nop 0
	v_mul_f32_e32 v149, 0x45800000, v148
	v_cndmask_b32_e32 v241, v148, v149, vcc
	v_ffbh_u32_e32 v160, v151
	v_min_u32_e32 v160, 32, v160
	v_lshlrev_b64 v[150:151], v160, v[150:151]
	v_min_u32_e32 v150, 1, v150
	v_or_b32_e32 v150, v151, v150
	v_cvt_f32_u32_e32 v150, v150
	v_sub_u32_e32 v151, 32, v160
	v_ldexp_f32 v150, v150, v151
	v_fmamk_f32 v150, v150, 0x30800000, v162
	v_cmp_gt_f32_e32 vcc, s95, v150
	v_mul_f32_e32 v151, 0x4b800000, v150
	s_nop 1
	v_cndmask_b32_e32 v150, v150, v151, vcc
	v_rsq_f32_e32 v150, v150
	s_nop 0
	v_mul_f32_e32 v151, 0x45800000, v150
	v_cndmask_b32_e32 v242, v150, v151, vcc
	v_ffbh_u32_e32 v160, v153
	v_min_u32_e32 v160, 32, v160
	v_lshlrev_b64 v[152:153], v160, v[152:153]
	v_min_u32_e32 v152, 1, v152
	v_or_b32_e32 v152, v153, v152
	v_cvt_f32_u32_e32 v152, v152
	v_sub_u32_e32 v153, 32, v160
	v_ldexp_f32 v152, v152, v153
	v_fmamk_f32 v152, v152, 0x30800000, v162
	v_cmp_gt_f32_e32 vcc, s95, v152
	v_mul_f32_e32 v153, 0x4b800000, v152
	s_nop 1
	v_cndmask_b32_e32 v152, v152, v153, vcc
	v_rsq_f32_e32 v152, v152
	s_nop 0
	v_mul_f32_e32 v153, 0x45800000, v152
	v_cndmask_b32_e32 v243, v152, v153, vcc
	v_ffbh_u32_e32 v160, v155
	v_min_u32_e32 v160, 32, v160
	v_lshlrev_b64 v[154:155], v160, v[154:155]
	v_min_u32_e32 v154, 1, v154
	v_or_b32_e32 v154, v155, v154
	v_cvt_f32_u32_e32 v154, v154
	v_sub_u32_e32 v155, 32, v160
	v_ldexp_f32 v154, v154, v155
	v_fmamk_f32 v154, v154, 0x30800000, v162
	v_cmp_gt_f32_e32 vcc, s95, v154
	v_mul_f32_e32 v155, 0x4b800000, v154
	s_nop 1
	v_cndmask_b32_e32 v154, v154, v155, vcc
	v_rsq_f32_e32 v154, v154
	s_nop 0
	v_mul_f32_e32 v155, 0x45800000, v154
	v_cndmask_b32_e32 v246, v154, v155, vcc
	v_ffbh_u32_e32 v160, v157
	v_min_u32_e32 v160, 32, v160
	v_lshlrev_b64 v[156:157], v160, v[156:157]
	v_min_u32_e32 v156, 1, v156
	v_or_b32_e32 v156, v157, v156
	v_cvt_f32_u32_e32 v156, v156
	v_sub_u32_e32 v157, 32, v160
	v_ldexp_f32 v156, v156, v157
	v_fmamk_f32 v156, v156, 0x30800000, v162
	v_cmp_gt_f32_e32 vcc, s95, v156
	v_mul_f32_e32 v157, 0x4b800000, v156
	s_nop 1
	v_cndmask_b32_e32 v156, v156, v157, vcc
	v_rsq_f32_e32 v156, v156
	s_nop 0
	v_mul_f32_e32 v157, 0x45800000, v156
	v_cndmask_b32_e32 v247, v156, v157, vcc
	v_ffbh_u32_e32 v160, v159
	v_min_u32_e32 v160, 32, v160
	v_lshlrev_b64 v[158:159], v160, v[158:159]
	v_min_u32_e32 v158, 1, v158
	v_or_b32_e32 v158, v159, v158
	v_cvt_f32_u32_e32 v158, v158
	v_sub_u32_e32 v159, 32, v160
	v_ldexp_f32 v158, v158, v159
	v_fmamk_f32 v158, v158, 0x30800000, v162
	v_cmp_gt_f32_e32 vcc, s95, v158
	v_mul_f32_e32 v159, 0x4b800000, v158
	s_nop 1
	v_cndmask_b32_e32 v158, v158, v159, vcc
	v_rsq_f32_e32 v158, v158
	s_nop 0
	v_mul_f32_e32 v159, 0x45800000, v158
	v_cndmask_b32_e32 v248, v158, v159, vcc

; #define PG8_STAGE(bufoff, gbase, voff) do { _Pragma("unroll") for (int _i = 0; _i < 2; ++_i) \
;         __builtin_amdgcn_global_load_lds((const unsigned*)((const char*)(gbase) + (voff)[_i]), (LAS unsigned*)(lds + (bufoff) + ldsw + _i * 8192), 16, 0, 0); } while (0)
; #define PG8_LDA(dst, b, h) do { _Pragma("unroll") for (int m = 0; m < 4; ++m) _Pragma("unroll") for (int k = 0; k < 2; ++k) dst[m][k] = *(const LAS bf16x8*)(lds + PG8_SA(b, h) + aoff + m * 2048 + k * 1024); } while (0)
; #define PG8_WAIT_V(n) asm volatile("s_waitcnt vmcnt(" #n ")" ::: "memory")
; #define PG8_WAIT_L(n) asm volatile("s_waitcnt lgkmcnt(" #n ")" ::: "memory")
; template <class Epi>
; __device__ __forceinline__ void gemm_phase(LAS unsigned char* lds, const Gemm g, const StaticOrder& S, const Epi& E) {
;     ...
;         for (int t = 0; t < nt; t += 2) {
;             const bool last = (t == nt - 2);
;             const char* a1 = cA + (size_t)(t + 1) * kstep;
;             const char* a2 = last ? nA : cA + (size_t)(t + 2) * kstep; const char* b2 = last ? nB : cB + (size_t)(t + 2) * kstep;
;             const char* a3 = a2 + kstep; const char* b3 = b2 + kstep;
;             PG8_LDB(B0, 0, 0); PG8_SCHED; PG8_LDA(At, 0, 0); PG8_STAGE(PG8_SA(1, 1), a1 + hstep, voffA);
;             PG8_WAIT_L(8); PG8_BAR; PG8_WAIT_L(0); PG8_MMA(0, 0, At, B0); PG8_BAR; PG8_SCHED;
;             PG8_LDB(B1, 0, 1); PG8_STAGE(PG8_SB(0, 0), b2, voffB);
;             PG8_BAR; PG8_WAIT_L(0); PG8_MMA(0, 1, At, B1); PG8_BAR;
;             PG8_LDA(At, 0, 1); PG8_STAGE(PG8_SA(0, 0), a2, voffA);
;             PG8_BAR; PG8_WAIT_L(0); PG8_MMA(1, 0, At, B0); PG8_BAR; PG8_SCHED;
;             PG8_STAGE(PG8_SB(0, 1), b2 + hstep, voffB);
;             PG8_WAIT_V(6); PG8_BAR; PG8_MMA(1, 1, At, B1); PG8_BAR;
;             PG8_LDB(B0, 1, 0); PG8_SCHED; PG8_LDA(At, 1, 0); PG8_STAGE(PG8_SA(0, 1), a2 + hstep, voffA);
;             PG8_WAIT_L(8); PG8_BAR; PG8_WAIT_L(0); PG8_MMA(0, 0, At, B0); PG8_BAR; PG8_SCHED;
;             PG8_LDB(B1, 1, 1); PG8_STAGE(PG8_SB(1, 0), b3, voffB);
;             PG8_BAR; PG8_WAIT_L(0); PG8_MMA(0, 1, At, B1); PG8_BAR;
;             PG8_LDA(At, 1, 1); PG8_STAGE(PG8_SA(1, 0), a3, voffA);
;             PG8_BAR; PG8_WAIT_L(0); PG8_MMA(1, 0, At, B0); PG8_BAR; PG8_SCHED;
;             PG8_STAGE(PG8_SB(1, 1), b3 + hstep, voffB);
;             PG8_WAIT_V(6); PG8_BAR; PG8_MMA(1, 1, At, B1); PG8_BAR;
;         }
.LBB0_505:
	s_add_u32 s48, s46, 0xfffc0080
	s_addc_u32 s49, s47, -1
	s_add_i32 s63, 0, 0x10000
	v_add_u32_e32 v152, s63, v171
	ds_read_b128 v[140:143], v152
	ds_read_b128 v[144:147], v152 offset:1024
	ds_read_b128 v[148:151], v152 offset:2048
	ds_read_b128 v[152:155], v152 offset:3072
	s_cmp_eq_u32 s62, 12
	s_cselect_b32 s51, s39, s49
	s_cselect_b32 s50, s58, s48
	s_cselect_b32 s49, s1, s61
	s_cselect_b32 s48, s59, s60
	v_lshl_add_u64 v[160:161], s[46:47], 0, v[136:137]
	s_add_i32 m0, s24, 0xc000
	ds_read_b128 v[156:159], v179
	ds_read_b128 v[180:183], v179 offset:1024
	ds_read_b128 v[184:187], v179 offset:2048
	ds_read_b128 v[188:191], v179 offset:3072
	ds_read_b128 v[192:195], v179 offset:4096
	ds_read_b128 v[196:199], v179 offset:5120
	ds_read_b128 v[200:203], v179 offset:6144
	ds_read_b128 v[204:207], v179 offset:7168
	global_load_lds_dwordx4 v[160:161], off
	v_lshl_add_u64 v[160:161], s[46:47], 0, v[138:139]
	s_add_i32 m0, s24, 0xe000
	s_nop 0
	global_load_lds_dwordx4 v[160:161], off
	s_waitcnt lgkmcnt(8)
	s_barrier
	s_waitcnt lgkmcnt(0)
	s_setprio 1
	s_waitcnt lgkmcnt(0)
	v_mfma_f32_16x16x32_bf16 v[126:129], v[140:143], v[156:159], v[126:129]
	v_mfma_f32_16x16x32_bf16 v[122:125], v[148:151], v[156:159], v[122:125]
	v_mfma_f32_16x16x32_bf16 v[110:113], v[140:143], v[184:187], v[110:113]
	v_mfma_f32_16x16x32_bf16 v[106:109], v[148:151], v[184:187], v[106:109]
	v_mfma_f32_16x16x32_bf16 v[94:97], v[140:143], v[192:195], v[94:97]
	v_mfma_f32_16x16x32_bf16 v[90:93], v[148:151], v[192:195], v[90:93]
	v_mfma_f32_16x16x32_bf16 v[78:81], v[140:143], v[200:203], v[78:81]
	v_mfma_f32_16x16x32_bf16 v[74:77], v[148:151], v[200:203], v[74:77]
	v_mfma_f32_16x16x32_bf16 v[126:129], v[144:147], v[180:183], v[126:129]
	v_mfma_f32_16x16x32_bf16 v[122:125], v[152:155], v[180:183], v[122:125]
	v_mfma_f32_16x16x32_bf16 v[110:113], v[144:147], v[188:191], v[110:113]
	v_mfma_f32_16x16x32_bf16 v[106:109], v[152:155], v[188:191], v[106:109]
	v_mfma_f32_16x16x32_bf16 v[94:97], v[144:147], v[196:199], v[94:97]
	v_mfma_f32_16x16x32_bf16 v[90:93], v[152:155], v[196:199], v[90:93]
	v_mfma_f32_16x16x32_bf16 v[78:81], v[144:147], v[204:207], v[78:81]
	v_mfma_f32_16x16x32_bf16 v[74:77], v[152:155], v[204:207], v[74:77]
	s_setprio 0
	s_barrier
	s_add_i32 s66, 0, 0x14000
	v_add_u32_e32 v160, s66, v171
	s_add_i32 s63, s63, s3
	ds_read_b128 v[208:211], v160
	ds_read_b128 v[212:215], v160 offset:1024
	ds_read_b128 v[216:219], v160 offset:2048
	ds_read_b128 v[220:223], v160 offset:3072
	v_lshl_add_u64 v[160:161], s[48:49], 0, v[0:1]
	s_mov_b32 m0, s63
	v_lshl_add_u64 v[172:173], s[48:49], 0, v[130:131]
	global_load_lds_dwordx4 v[160:161], off
	s_add_i32 m0, s63, 0x2000
	s_nop 0
	global_load_lds_dwordx4 v[172:173], off
	s_barrier
	s_waitcnt lgkmcnt(0)
	s_setprio 1
	s_waitcnt lgkmcnt(0)
	v_mfma_f32_16x16x32_bf16 v[118:121], v[208:211], v[156:159], v[118:121]
	v_mfma_f32_16x16x32_bf16 v[114:117], v[216:219], v[156:159], v[114:117]
	v_mfma_f32_16x16x32_bf16 v[102:105], v[208:211], v[184:187], v[102:105]
	v_mfma_f32_16x16x32_bf16 v[98:101], v[216:219], v[184:187], v[98:101]
	v_mfma_f32_16x16x32_bf16 v[86:89], v[208:211], v[192:195], v[86:89]
	v_mfma_f32_16x16x32_bf16 v[82:85], v[216:219], v[192:195], v[82:85]
	v_mfma_f32_16x16x32_bf16 v[70:73], v[208:211], v[200:203], v[70:73]
	v_mfma_f32_16x16x32_bf16 v[66:69], v[216:219], v[200:203], v[66:69]
	v_mfma_f32_16x16x32_bf16 v[118:121], v[212:215], v[180:183], v[118:121]
	v_mfma_f32_16x16x32_bf16 v[114:117], v[220:223], v[180:183], v[114:117]
	v_mfma_f32_16x16x32_bf16 v[102:105], v[212:215], v[188:191], v[102:105]
	v_mfma_f32_16x16x32_bf16 v[98:101], v[220:223], v[188:191], v[98:101]
	v_mfma_f32_16x16x32_bf16 v[86:89], v[212:215], v[196:199], v[86:89]
	v_mfma_f32_16x16x32_bf16 v[82:85], v[220:223], v[196:199], v[82:85]
	v_mfma_f32_16x16x32_bf16 v[70:73], v[212:215], v[204:207], v[70:73]
	v_mfma_f32_16x16x32_bf16 v[66:69], v[220:223], v[204:207], v[66:69]
	s_setprio 0
	s_mov_b32 m0, s24
	v_lshl_add_u64 v[174:175], s[50:51], 0, v[134:135]
	s_barrier
	ds_read_b128 v[156:159], v179 offset:16384
	ds_read_b128 v[180:183], v179 offset:17408
	ds_read_b128 v[184:187], v179 offset:18432
	ds_read_b128 v[188:191], v179 offset:19456
	ds_read_b128 v[192:195], v179 offset:20480
	ds_read_b128 v[196:199], v179 offset:21504
	ds_read_b128 v[200:203], v179 offset:22528
	ds_read_b128 v[204:207], v179 offset:23552
	global_load_lds_dwordx4 v[174:175], off
	v_lshl_add_u64 v[176:177], s[50:51], 0, v[132:133]
	s_mov_b32 m0, s26
	s_nop 0
	global_load_lds_dwordx4 v[176:177], off
	s_barrier
	s_waitcnt lgkmcnt(0)
	s_setprio 1
	s_waitcnt lgkmcnt(0)
	v_mfma_f32_16x16x32_bf16 v[62:65], v[140:143], v[156:159], v[62:65]
	v_mfma_f32_16x16x32_bf16 v[58:61], v[148:151], v[156:159], v[58:61]
	v_mfma_f32_16x16x32_bf16 v[46:49], v[140:143], v[184:187], v[46:49]
	v_mfma_f32_16x16x32_bf16 v[42:45], v[148:151], v[184:187], v[42:45]
	v_mfma_f32_16x16x32_bf16 v[30:33], v[140:143], v[192:195], v[30:33]
	v_mfma_f32_16x16x32_bf16 v[26:29], v[148:151], v[192:195], v[26:29]
	v_mfma_f32_16x16x32_bf16 v[14:17], v[140:143], v[200:203], v[14:17]
	v_mfma_f32_16x16x32_bf16 v[10:13], v[148:151], v[200:203], v[10:13]
	v_mfma_f32_16x16x32_bf16 v[62:65], v[144:147], v[180:183], v[62:65]
	v_mfma_f32_16x16x32_bf16 v[58:61], v[152:155], v[180:183], v[58:61]
	v_mfma_f32_16x16x32_bf16 v[46:49], v[144:147], v[188:191], v[46:49]
	v_mfma_f32_16x16x32_bf16 v[42:45], v[152:155], v[188:191], v[42:45]
	v_mfma_f32_16x16x32_bf16 v[30:33], v[144:147], v[196:199], v[30:33]
	v_mfma_f32_16x16x32_bf16 v[26:29], v[152:155], v[196:199], v[26:29]
	v_mfma_f32_16x16x32_bf16 v[14:17], v[144:147], v[204:207], v[14:17]
	v_mfma_f32_16x16x32_bf16 v[10:13], v[152:155], v[204:207], v[10:13]
	s_setprio 0
	s_barrier
; #define PG8_STAGE(bufoff, gbase, voff) do { _Pragma("unroll") for (int _i = 0; _i < 2; ++_i) \
;         __builtin_amdgcn_global_load_lds((const unsigned*)((const char*)(gbase) + (voff)[_i]), (LAS unsigned*)(lds + (bufoff) + ldsw + _i * 8192), 16, 0, 0); } while (0)
; #define PG8_LDA(dst, b, h) do { _Pragma("unroll") for (int m = 0; m < 4; ++m) _Pragma("unroll") for (int k = 0; k < 2; ++k) dst[m][k] = *(const LAS bf16x8*)(lds + PG8_SA(b, h) + aoff + m * 2048 + k * 1024); } while (0)
; #define PG8_LDB(dst, b, h) do { _Pragma("unroll") for (int n = 0; n < 2; ++n) _Pragma("unroll") for (int k = 0; k < 2; ++k) dst[n][k] = *(const LAS bf16x8*)(lds + PG8_SB(b, h) + boff + n * 2048 + k * 1024); } while (0)
; #define PG8_WAIT_V(n) asm volatile("s_waitcnt vmcnt(" #n ")" ::: "memory")
; #define PG8_WAIT_L(n) asm volatile("s_waitcnt lgkmcnt(" #n ")" ::: "memory")
; #define PG8_BAR __builtin_amdgcn_s_barrier()
; #define PG8_SCHED __builtin_amdgcn_sched_barrier(0)
; template <class Epi>
; __device__ __forceinline__ void gemm_phase(LAS unsigned char* lds, const Gemm g, const StaticOrder& S, const Epi& E) {
;     ...
;             PG8_LDB(B0, 0, 0); PG8_SCHED; PG8_LDA(At, 0, 0); PG8_STAGE(PG8_SA(1, 1), a1 + hstep, voffA);
;             PG8_WAIT_L(8); PG8_BAR; PG8_WAIT_L(0); PG8_MMA(0, 0, At, B0); PG8_BAR; PG8_SCHED;
;             PG8_LDB(B1, 0, 1); PG8_STAGE(PG8_SB(0, 0), b2, voffB);
;             PG8_BAR; PG8_WAIT_L(0); PG8_MMA(0, 1, At, B1); PG8_BAR;
;             PG8_LDA(At, 0, 1); PG8_STAGE(PG8_SA(0, 0), a2, voffA);
;             PG8_BAR; PG8_WAIT_L(0); PG8_MMA(1, 0, At, B0); PG8_BAR; PG8_SCHED;
;             PG8_STAGE(PG8_SB(0, 1), b2 + hstep, voffB);
;             PG8_WAIT_V(6); PG8_BAR; PG8_MMA(1, 1, At, B1); PG8_BAR;
;             PG8_LDB(B0, 1, 0); PG8_SCHED; PG8_LDA(At, 1, 0); PG8_STAGE(PG8_SA(0, 1), a2 + hstep, voffA);
;             PG8_WAIT_L(8); PG8_BAR; PG8_WAIT_L(0); PG8_MMA(0, 0, At, B0); PG8_BAR; PG8_SCHED;
;             PG8_LDB(B1, 1, 1); PG8_STAGE(PG8_SB(1, 0), b3, voffB);
;             PG8_BAR; PG8_WAIT_L(0); PG8_MMA(0, 1, At, B1); PG8_BAR;
;             PG8_LDA(At, 1, 1); PG8_STAGE(PG8_SA(1, 0), a3, voffA);
;             PG8_BAR; PG8_WAIT_L(0); PG8_MMA(1, 0, At, B0); PG8_BAR; PG8_SCHED;
;             PG8_STAGE(PG8_SB(1, 1), b3 + hstep, voffB);
;             PG8_WAIT_V(6); PG8_BAR; PG8_MMA(1, 1, At, B1); PG8_BAR;
	s_add_u32 s64, s48, 0x40000
	s_addc_u32 s65, s49, 0
	s_add_i32 s63, s66, s3
	v_lshl_add_u64 v[140:141], s[64:65], 0, v[0:1]
	s_mov_b32 m0, s63
	s_nop 0
	global_load_lds_dwordx4 v[140:141], off
	v_lshl_add_u64 v[140:141], s[64:65], 0, v[130:131]
	s_add_i32 m0, s63, 0x2000
	s_nop 0
	global_load_lds_dwordx4 v[140:141], off
	s_waitcnt vmcnt(6)
	s_barrier
	s_setprio 1
	v_mfma_f32_16x16x32_bf16 v[54:57], v[208:211], v[156:159], v[54:57]
	v_mfma_f32_16x16x32_bf16 v[50:53], v[216:219], v[156:159], v[50:53]
	v_mfma_f32_16x16x32_bf16 v[38:41], v[208:211], v[184:187], v[38:41]
	v_mfma_f32_16x16x32_bf16 v[34:37], v[216:219], v[184:187], v[34:37]
	v_mfma_f32_16x16x32_bf16 v[22:25], v[208:211], v[192:195], v[22:25]
	v_mfma_f32_16x16x32_bf16 v[18:21], v[216:219], v[192:195], v[18:21]
	v_mfma_f32_16x16x32_bf16 v[6:9], v[208:211], v[200:203], v[6:9]
	v_mfma_f32_16x16x32_bf16 v[2:5], v[216:219], v[200:203], v[2:5]
	v_mfma_f32_16x16x32_bf16 v[54:57], v[212:215], v[180:183], v[54:57]
	v_mfma_f32_16x16x32_bf16 v[50:53], v[220:223], v[180:183], v[50:53]
	v_mfma_f32_16x16x32_bf16 v[38:41], v[212:215], v[188:191], v[38:41]
	v_mfma_f32_16x16x32_bf16 v[34:37], v[220:223], v[188:191], v[34:37]
	v_mfma_f32_16x16x32_bf16 v[22:25], v[212:215], v[196:199], v[22:25]
	v_mfma_f32_16x16x32_bf16 v[18:21], v[220:223], v[196:199], v[18:21]
	v_mfma_f32_16x16x32_bf16 v[6:9], v[212:215], v[204:207], v[6:9]
	v_mfma_f32_16x16x32_bf16 v[2:5], v[220:223], v[204:207], v[2:5]
	s_setprio 0
	s_add_i32 s63, 0, 0x18000
	v_add_u32_e32 v152, s63, v171
	s_barrier
	ds_read_b128 v[140:143], v152
	ds_read_b128 v[144:147], v152 offset:1024
	ds_read_b128 v[148:151], v152 offset:2048
	ds_read_b128 v[152:155], v152 offset:3072
	s_add_u32 s50, s50, 0x40000
	s_addc_u32 s51, s51, 0
	s_mov_b32 m0, s30
	v_lshl_add_u64 v[208:209], s[50:51], 0, v[134:135]
	ds_read_b128 v[156:159], v179 offset:32768
	ds_read_b128 v[180:183], v179 offset:33792
	ds_read_b128 v[184:187], v179 offset:34816
	ds_read_b128 v[188:191], v179 offset:35840
	ds_read_b128 v[192:195], v179 offset:36864
	ds_read_b128 v[196:199], v179 offset:37888
	ds_read_b128 v[200:203], v179 offset:38912
	ds_read_b128 v[204:207], v179 offset:39936
	global_load_lds_dwordx4 v[208:209], off
	v_lshl_add_u64 v[208:209], s[50:51], 0, v[132:133]
	s_mov_b32 m0, s52
	s_nop 0
	global_load_lds_dwordx4 v[208:209], off
	s_waitcnt lgkmcnt(8)
	s_barrier
	s_waitcnt lgkmcnt(0)
	s_setprio 1
	s_waitcnt lgkmcnt(0)
	v_mfma_f32_16x16x32_bf16 v[126:129], v[140:143], v[156:159], v[126:129]
	v_mfma_f32_16x16x32_bf16 v[122:125], v[148:151], v[156:159], v[122:125]
	v_mfma_f32_16x16x32_bf16 v[110:113], v[140:143], v[184:187], v[110:113]
	v_mfma_f32_16x16x32_bf16 v[106:109], v[148:151], v[184:187], v[106:109]
	v_mfma_f32_16x16x32_bf16 v[94:97], v[140:143], v[192:195], v[94:97]
	v_mfma_f32_16x16x32_bf16 v[90:93], v[148:151], v[192:195], v[90:93]
	v_mfma_f32_16x16x32_bf16 v[78:81], v[140:143], v[200:203], v[78:81]
	v_mfma_f32_16x16x32_bf16 v[74:77], v[148:151], v[200:203], v[74:77]
	v_mfma_f32_16x16x32_bf16 v[126:129], v[144:147], v[180:183], v[126:129]
	v_mfma_f32_16x16x32_bf16 v[122:125], v[152:155], v[180:183], v[122:125]
	v_mfma_f32_16x16x32_bf16 v[110:113], v[144:147], v[188:191], v[110:113]
	v_mfma_f32_16x16x32_bf16 v[106:109], v[152:155], v[188:191], v[106:109]
	v_mfma_f32_16x16x32_bf16 v[94:97], v[144:147], v[196:199], v[94:97]
	v_mfma_f32_16x16x32_bf16 v[90:93], v[152:155], v[196:199], v[90:93]
	v_mfma_f32_16x16x32_bf16 v[78:81], v[144:147], v[204:207], v[78:81]
	v_mfma_f32_16x16x32_bf16 v[74:77], v[152:155], v[204:207], v[74:77]
	s_setprio 0
	s_barrier
	s_add_i32 s50, 0, 0x1c000
	s_add_i32 s51, s63, s3
	v_add_u32_e32 v220, s50, v171
	v_lshl_add_u64 v[160:161], v[160:161], 0, s[28:29]
	s_mov_b32 m0, s51
	ds_read_b128 v[208:211], v220
	ds_read_b128 v[212:215], v220 offset:1024
	ds_read_b128 v[216:219], v220 offset:2048
	ds_read_b128 v[220:223], v220 offset:3072
	global_load_lds_dwordx4 v[160:161], off
	v_lshl_add_u64 v[160:161], v[172:173], 0, s[28:29]
	s_add_i32 m0, s51, 0x2000
	s_nop 0
	global_load_lds_dwordx4 v[160:161], off
	s_barrier
	s_waitcnt lgkmcnt(0)
	s_setprio 1
	s_waitcnt lgkmcnt(0)
	v_mfma_f32_16x16x32_bf16 v[118:121], v[208:211], v[156:159], v[118:121]
	v_mfma_f32_16x16x32_bf16 v[114:117], v[216:219], v[156:159], v[114:117]
	v_mfma_f32_16x16x32_bf16 v[102:105], v[208:211], v[184:187], v[102:105]
	v_mfma_f32_16x16x32_bf16 v[98:101], v[216:219], v[184:187], v[98:101]
	v_mfma_f32_16x16x32_bf16 v[86:89], v[208:211], v[192:195], v[86:89]
	v_mfma_f32_16x16x32_bf16 v[82:85], v[216:219], v[192:195], v[82:85]
	v_mfma_f32_16x16x32_bf16 v[70:73], v[208:211], v[200:203], v[70:73]
	v_mfma_f32_16x16x32_bf16 v[66:69], v[216:219], v[200:203], v[66:69]
	v_mfma_f32_16x16x32_bf16 v[118:121], v[212:215], v[180:183], v[118:121]
	v_mfma_f32_16x16x32_bf16 v[114:117], v[220:223], v[180:183], v[114:117]
	v_mfma_f32_16x16x32_bf16 v[102:105], v[212:215], v[188:191], v[102:105]
	v_mfma_f32_16x16x32_bf16 v[98:101], v[220:223], v[188:191], v[98:101]
	v_mfma_f32_16x16x32_bf16 v[86:89], v[212:215], v[196:199], v[86:89]
	v_mfma_f32_16x16x32_bf16 v[82:85], v[220:223], v[196:199], v[82:85]
	v_mfma_f32_16x16x32_bf16 v[70:73], v[212:215], v[204:207], v[70:73]
	v_mfma_f32_16x16x32_bf16 v[66:69], v[220:223], v[204:207], v[66:69]
	s_setprio 0
	s_mov_b32 m0, s53
	v_lshl_add_u64 v[160:161], v[174:175], 0, s[28:29]
	s_barrier
	ds_read_b128 v[156:159], v179 offset:49152
	ds_read_b128 v[180:183], v179 offset:50176
	ds_read_b128 v[184:187], v179 offset:51200
	ds_read_b128 v[188:191], v179 offset:52224
	ds_read_b128 v[192:195], v179 offset:53248
	ds_read_b128 v[196:199], v179 offset:54272
	ds_read_b128 v[200:203], v179 offset:55296
	ds_read_b128 v[204:207], v179 offset:56320
	global_load_lds_dwordx4 v[160:161], off
	v_lshl_add_u64 v[160:161], v[176:177], 0, s[28:29]
	s_mov_b32 m0, s54
	s_nop 0
	global_load_lds_dwordx4 v[160:161], off
	s_barrier
; __device__ __forceinline__ float rstd_fix(u64 v) { return rsqrtf((float)v * (1.f / (1048576.f * 1024.f)) + 1e-6f); }
; __device__ __forceinline__ unsigned pk2(float lo, float hi) { unsigned r; asm volatile("v_cvt_pk_bf16_f32 %0, %1, %2" : "=v"(r) : "v"(lo), "v"(hi)); return r; }
; #define PG8_MMA(ai, bj, At, Bt) do { __builtin_amdgcn_s_setprio(1); _Pragma("unroll") for (int m = 0; m < 4; ++m) _Pragma("unroll") for (int n = 0; n < 2; ++n) _Pragma("unroll") for (int k = 0; k < 2; ++k) \
;         acc[ai][bj][m][n] = __builtin_amdgcn_mfma_f32_16x16x32_bf16(Bt[n][k], At[m][k], acc[ai][bj][m][n], 0, 0, 0); __builtin_amdgcn_s_setprio(0); } while (0)
; #define PG8_WAIT_V(n) asm volatile("s_waitcnt vmcnt(" #n ")" ::: "memory")
; #define PG8_BAR __builtin_amdgcn_s_barrier()
; template <class Epi>
; __device__ __forceinline__ void gemm_phase(LAS unsigned char* lds, const Gemm g, const StaticOrder& S, const Epi& E) {
;     ...
;             PG8_WAIT_V(6); PG8_BAR; PG8_MMA(1, 1, At, B1); PG8_BAR;
;         }
;     __device__ __forceinline__ void operator()(const f32x4 (&acc)[2][2][4][2], const Unit& u, int wr, int wc, int fr, int fq) const {
;         const int row0 = u.pm * BM + wr * 64 + fr, col0 = u.pn * BM + wc * 32 + 8 * fq;
;         u64 rv[2][4];
; #pragma unroll
;         for (int ai = 0; ai < 2; ++ai)
; #pragma unroll
;             for (int m = 0; m < 4; ++m) rv[ai][m] = rss[row0 + ai * HALF + m * 16];
; #pragma unroll
;         for (int ai = 0; ai < 2; ++ai)
; #pragma unroll
;             for (int m = 0; m < 4; ++m) { const int row = row0 + ai * HALF + m * 16; bf16_t* rowp = O + (size_t)row * ldc + col0;
;                 const float rs = rstd_fix(rv[ai][m]);
; #pragma unroll
;                 for (int bj = 0; bj < 2; ++bj) { const f32x4 v0 = acc[ai][bj][m][0] * rs, v1 = acc[ai][bj][m][1] * rs;
;                     u32x4 w; w.x = pk2(v0[0], v0[1]); w.y = pk2(v0[2], v0[3]); w.z = pk2(v1[0], v1[1]); w.w = pk2(v1[2], v1[3]);
;                     *(u32x4*)(rowp + bj * HALF) = w; } }
	s_waitcnt lgkmcnt(0)
	s_setprio 1
	s_waitcnt lgkmcnt(0)
	v_mfma_f32_16x16x32_bf16 v[62:65], v[140:143], v[156:159], v[62:65]
	v_mfma_f32_16x16x32_bf16 v[58:61], v[148:151], v[156:159], v[58:61]
	v_mfma_f32_16x16x32_bf16 v[46:49], v[140:143], v[184:187], v[46:49]
	v_mfma_f32_16x16x32_bf16 v[42:45], v[148:151], v[184:187], v[42:45]
	v_mfma_f32_16x16x32_bf16 v[30:33], v[140:143], v[192:195], v[30:33]
	v_mfma_f32_16x16x32_bf16 v[26:29], v[148:151], v[192:195], v[26:29]
	v_mfma_f32_16x16x32_bf16 v[14:17], v[140:143], v[200:203], v[14:17]
	v_mfma_f32_16x16x32_bf16 v[10:13], v[148:151], v[200:203], v[10:13]
	v_mfma_f32_16x16x32_bf16 v[62:65], v[144:147], v[180:183], v[62:65]
	v_mfma_f32_16x16x32_bf16 v[58:61], v[152:155], v[180:183], v[58:61]
	v_mfma_f32_16x16x32_bf16 v[46:49], v[144:147], v[188:191], v[46:49]
	v_mfma_f32_16x16x32_bf16 v[42:45], v[152:155], v[188:191], v[42:45]
	v_mfma_f32_16x16x32_bf16 v[30:33], v[144:147], v[196:199], v[30:33]
	v_mfma_f32_16x16x32_bf16 v[26:29], v[152:155], v[196:199], v[26:29]
	v_mfma_f32_16x16x32_bf16 v[14:17], v[144:147], v[204:207], v[14:17]
	v_mfma_f32_16x16x32_bf16 v[10:13], v[152:155], v[204:207], v[10:13]
	s_setprio 0
	s_barrier
	s_add_u32 s48, s48, 0x40080
	s_addc_u32 s49, s49, 0
	s_add_i32 s50, s50, s3
	v_lshl_add_u64 v[140:141], s[48:49], 0, v[0:1]
	s_mov_b32 m0, s50
	s_nop 0
	global_load_lds_dwordx4 v[140:141], off
	v_lshl_add_u64 v[140:141], s[48:49], 0, v[130:131]
	s_add_i32 m0, s50, 0x2000
	s_nop 0
	global_load_lds_dwordx4 v[140:141], off
	s_waitcnt vmcnt(6)
	s_barrier
	s_setprio 1
	v_mfma_f32_16x16x32_bf16 v[54:57], v[208:211], v[156:159], v[54:57]
	v_mfma_f32_16x16x32_bf16 v[50:53], v[216:219], v[156:159], v[50:53]
	v_mfma_f32_16x16x32_bf16 v[38:41], v[208:211], v[184:187], v[38:41]
	v_mfma_f32_16x16x32_bf16 v[34:37], v[216:219], v[184:187], v[34:37]
	v_mfma_f32_16x16x32_bf16 v[22:25], v[208:211], v[192:195], v[22:25]
	v_mfma_f32_16x16x32_bf16 v[18:21], v[216:219], v[192:195], v[18:21]
	v_mfma_f32_16x16x32_bf16 v[6:9], v[208:211], v[200:203], v[6:9]
	v_mfma_f32_16x16x32_bf16 v[2:5], v[216:219], v[200:203], v[2:5]
	v_mfma_f32_16x16x32_bf16 v[54:57], v[212:215], v[180:183], v[54:57]
	v_mfma_f32_16x16x32_bf16 v[50:53], v[220:223], v[180:183], v[50:53]
	v_mfma_f32_16x16x32_bf16 v[38:41], v[212:215], v[188:191], v[38:41]
	v_mfma_f32_16x16x32_bf16 v[34:37], v[220:223], v[188:191], v[34:37]
	v_mfma_f32_16x16x32_bf16 v[22:25], v[212:215], v[196:199], v[22:25]
	v_mfma_f32_16x16x32_bf16 v[18:21], v[220:223], v[196:199], v[18:21]
	v_mfma_f32_16x16x32_bf16 v[6:9], v[212:215], v[204:207], v[6:9]
	v_mfma_f32_16x16x32_bf16 v[2:5], v[220:223], v[204:207], v[2:5]
	s_setprio 0
	s_add_i32 s62, s62, 2
	s_add_u32 s46, s46, 0x100
	s_addc_u32 s47, s47, 0
	s_add_u32 s60, s60, 0x100
	s_addc_u32 s61, s61, 0
	s_cmp_gt_u32 s62, 13
	s_barrier
	s_cbranch_scc0 .LBB0_505
	v_lshl_add_u32 v142, s57, 8, v168
	v_ashrrev_i32_e32 v143, 31, v142
	s_nop 0
	v_lshl_or_b32 v154, s56, 8, v178
	v_or_b32_e32 v160, 16, v142
	v_or_b32_e32 v158, 32, v142
	v_or_b32_e32 v152, 48, v142
	v_ashrrev_i32_e32 v155, 31, v154
	v_lshlrev_b64 v[142:143], 13, v[142:143]
	v_lshl_add_u64 v[142:143], s[34:35], 0, v[142:143]
	v_lshlrev_b64 v[154:155], 1, v[154:155]
	v_lshl_add_u64 v[142:143], v[142:143], 0, v[154:155]
	v_ashrrev_i32_e32 v161, 31, v160
	v_ashrrev_i32_e32 v159, 31, v158
	v_ashrrev_i32_e32 v153, 31, v152
	s_mov_b32 s1, 0x100000
	s_mov_b64 s[46:47], 0x100000
	s_mov_b32 s56, s0
	s_mov_b32 s57, s38
	s_mov_b64 s[48:49], s[44:45]
	v_mov_b32_e32 v172, v236
	s_nop 0
	s_nop 0
	v_pk_mul_f32 v[128:129], v[128:129], v[172:173] op_sel_hi:[1,0]
	v_pk_mul_f32 v[126:127], v[126:127], v[172:173] op_sel_hi:[1,0]
	v_pk_mul_f32 v[174:175], v[124:125], v[172:173] op_sel_hi:[1,0]
	v_pk_mul_f32 v[124:125], v[122:123], v[172:173] op_sel_hi:[1,0]
	v_cvt_pk_bf16_f32 v122, v126, v127
	v_cvt_pk_bf16_f32 v123, v128, v129
	v_pk_mul_f32 v[120:121], v[120:121], v[172:173] op_sel_hi:[1,0]
	v_cvt_pk_bf16_f32 v124, v124, v125
	v_cvt_pk_bf16_f32 v125, v174, v175
	global_store_dwordx4 v[142:143], v[122:125], off
	v_pk_mul_f32 v[118:119], v[118:119], v[172:173] op_sel_hi:[1,0]
	s_nop 0
	v_pk_mul_f32 v[122:123], v[116:117], v[172:173] op_sel_hi:[1,0]
	v_pk_mul_f32 v[116:117], v[114:115], v[172:173] op_sel_hi:[1,0]
	v_cvt_pk_bf16_f32 v114, v118, v119
	v_cvt_pk_bf16_f32 v115, v120, v121
	s_nop 0
	v_cvt_pk_bf16_f32 v116, v116, v117
	v_cvt_pk_bf16_f32 v117, v122, v123
	global_store_dwordx4 v[142:143], v[114:117], off offset:256
	s_nop 1
	v_mov_b32_e32 v116, v237
	v_lshlrev_b64 v[114:115], 13, v[160:161]
	v_lshl_add_u64 v[114:115], s[34:35], 0, v[114:115]
	v_lshl_add_u64 v[114:115], v[114:115], 0, v[154:155]
	s_nop 0
	v_pk_mul_f32 v[112:113], v[112:113], v[116:117] op_sel_hi:[1,0]
	v_pk_mul_f32 v[110:111], v[110:111], v[116:117] op_sel_hi:[1,0]
	v_pk_mul_f32 v[118:119], v[108:109], v[116:117] op_sel_hi:[1,0]
	v_pk_mul_f32 v[108:109], v[106:107], v[116:117] op_sel_hi:[1,0]
	v_cvt_pk_bf16_f32 v106, v110, v111
	v_cvt_pk_bf16_f32 v107, v112, v113
	v_pk_mul_f32 v[104:105], v[104:105], v[116:117] op_sel_hi:[1,0]
	v_cvt_pk_bf16_f32 v108, v108, v109
	v_cvt_pk_bf16_f32 v109, v118, v119
	global_store_dwordx4 v[114:115], v[106:109], off
	v_pk_mul_f32 v[102:103], v[102:103], v[116:117] op_sel_hi:[1,0]
	s_nop 0
	v_pk_mul_f32 v[106:107], v[100:101], v[116:117] op_sel_hi:[1,0]
	v_pk_mul_f32 v[100:101], v[98:99], v[116:117] op_sel_hi:[1,0]
	v_cvt_pk_bf16_f32 v98, v102, v103
	v_cvt_pk_bf16_f32 v99, v104, v105
	s_nop 0
	v_cvt_pk_bf16_f32 v100, v100, v101
	v_cvt_pk_bf16_f32 v101, v106, v107
	global_store_dwordx4 v[114:115], v[98:101], off offset:256
	s_nop 1
	v_mov_b32_e32 v100, v241
; __device__ __forceinline__ float rstd_fix(u64 v) { return rsqrtf((float)v * (1.f / (1048576.f * 1024.f)) + 1e-6f); }
; __device__ __forceinline__ unsigned pk2(float lo, float hi) { unsigned r; asm volatile("v_cvt_pk_bf16_f32 %0, %1, %2" : "=v"(r) : "v"(lo), "v"(hi)); return r; }
;     __device__ __forceinline__ void operator()(const f32x4 (&acc)[2][2][4][2], const Unit& u, int wr, int wc, int fr, int fq) const {
;     ...
;         for (int ai = 0; ai < 2; ++ai)
; #pragma unroll
;             for (int m = 0; m < 4; ++m) { const int row = row0 + ai * HALF + m * 16; bf16_t* rowp = O + (size_t)row * ldc + col0;
;                 const float rs = rstd_fix(rv[ai][m]);
; #pragma unroll
;                 for (int bj = 0; bj < 2; ++bj) { const f32x4 v0 = acc[ai][bj][m][0] * rs, v1 = acc[ai][bj][m][1] * rs;
;                     u32x4 w; w.x = pk2(v0[0], v0[1]); w.y = pk2(v0[2], v0[3]); w.z = pk2(v1[0], v1[1]); w.w = pk2(v1[2], v1[3]);
;                     *(u32x4*)(rowp + bj * HALF) = w; } }
	v_lshlrev_b64 v[98:99], 13, v[158:159]
	v_lshl_add_u64 v[98:99], s[34:35], 0, v[98:99]
	v_lshl_add_u64 v[98:99], v[98:99], 0, v[154:155]
	s_nop 0
	v_pk_mul_f32 v[96:97], v[96:97], v[100:101] op_sel_hi:[1,0]
	v_pk_mul_f32 v[94:95], v[94:95], v[100:101] op_sel_hi:[1,0]
	v_pk_mul_f32 v[102:103], v[92:93], v[100:101] op_sel_hi:[1,0]
	v_pk_mul_f32 v[92:93], v[90:91], v[100:101] op_sel_hi:[1,0]
	v_cvt_pk_bf16_f32 v90, v94, v95
	v_cvt_pk_bf16_f32 v91, v96, v97
	v_pk_mul_f32 v[88:89], v[88:89], v[100:101] op_sel_hi:[1,0]
	v_cvt_pk_bf16_f32 v92, v92, v93
	v_cvt_pk_bf16_f32 v93, v102, v103
	global_store_dwordx4 v[98:99], v[90:93], off
	v_pk_mul_f32 v[86:87], v[86:87], v[100:101] op_sel_hi:[1,0]
	s_nop 0
	v_pk_mul_f32 v[90:91], v[84:85], v[100:101] op_sel_hi:[1,0]
	v_pk_mul_f32 v[84:85], v[82:83], v[100:101] op_sel_hi:[1,0]
	v_cvt_pk_bf16_f32 v82, v86, v87
	v_cvt_pk_bf16_f32 v83, v88, v89
	s_nop 0
	v_cvt_pk_bf16_f32 v84, v84, v85
	v_cvt_pk_bf16_f32 v85, v90, v91
	global_store_dwordx4 v[98:99], v[82:85], off offset:256
	s_nop 1
	v_mov_b32_e32 v84, v242
	v_lshlrev_b64 v[82:83], 13, v[152:153]
	v_lshl_add_u64 v[82:83], s[34:35], 0, v[82:83]
	v_lshl_add_u64 v[82:83], v[82:83], 0, v[154:155]
	s_nop 0
	v_pk_mul_f32 v[80:81], v[80:81], v[84:85] op_sel_hi:[1,0]
	v_pk_mul_f32 v[78:79], v[78:79], v[84:85] op_sel_hi:[1,0]
	v_pk_mul_f32 v[86:87], v[76:77], v[84:85] op_sel_hi:[1,0]
	v_pk_mul_f32 v[76:77], v[74:75], v[84:85] op_sel_hi:[1,0]
	v_cvt_pk_bf16_f32 v74, v78, v79
	v_cvt_pk_bf16_f32 v75, v80, v81
	v_pk_mul_f32 v[72:73], v[72:73], v[84:85] op_sel_hi:[1,0]
	v_cvt_pk_bf16_f32 v76, v76, v77
	v_cvt_pk_bf16_f32 v77, v86, v87
	global_store_dwordx4 v[82:83], v[74:77], off
	v_pk_mul_f32 v[70:71], v[70:71], v[84:85] op_sel_hi:[1,0]
	s_nop 0
	v_pk_mul_f32 v[74:75], v[68:69], v[84:85] op_sel_hi:[1,0]
	v_pk_mul_f32 v[68:69], v[66:67], v[84:85] op_sel_hi:[1,0]
	v_cvt_pk_bf16_f32 v66, v70, v71
	v_cvt_pk_bf16_f32 v67, v72, v73
	s_nop 0
	v_cvt_pk_bf16_f32 v68, v68, v69
	v_cvt_pk_bf16_f32 v69, v74, v75
	global_store_dwordx4 v[82:83], v[66:69], off offset:256
	s_nop 1
	v_mov_b32_e32 v68, v243
	v_lshl_add_u64 v[66:67], v[142:143], 0, s[46:47]
	s_mov_b64 s[46:47], 0x120000
	s_nop 0
	s_nop 0
	v_pk_mul_f32 v[62:63], v[62:63], v[68:69] op_sel_hi:[1,0]
	v_pk_mul_f32 v[70:71], v[60:61], v[68:69] op_sel_hi:[1,0]
	v_pk_mul_f32 v[60:61], v[58:59], v[68:69] op_sel_hi:[1,0]
	v_cvt_pk_bf16_f32 v58, v62, v63
	v_add_co_u32_e32 v62, vcc, s1, v142
	v_pk_mul_f32 v[64:65], v[64:65], v[68:69] op_sel_hi:[1,0]
	s_nop 0
	v_addc_co_u32_e32 v63, vcc, 0, v143, vcc
	v_cvt_pk_bf16_f32 v59, v64, v65
	v_cvt_pk_bf16_f32 v60, v60, v61
	v_cvt_pk_bf16_f32 v61, v70, v71
	global_store_dwordx4 v[62:63], v[58:61], off
	v_pk_mul_f32 v[56:57], v[56:57], v[68:69] op_sel_hi:[1,0]
	v_pk_mul_f32 v[54:55], v[54:55], v[68:69] op_sel_hi:[1,0]
	v_pk_mul_f32 v[58:59], v[52:53], v[68:69] op_sel_hi:[1,0]
	v_pk_mul_f32 v[52:53], v[50:51], v[68:69] op_sel_hi:[1,0]
	v_cvt_pk_bf16_f32 v50, v54, v55
	v_cvt_pk_bf16_f32 v51, v56, v57
	s_mov_b32 s1, 0x120000
	v_cvt_pk_bf16_f32 v52, v52, v53
	v_cvt_pk_bf16_f32 v53, v58, v59
	global_store_dwordx4 v[66:67], v[50:53], off offset:256
	s_nop 1
	v_mov_b32_e32 v52, v246
	v_lshl_add_u64 v[50:51], v[142:143], 0, s[46:47]
	s_mov_b64 s[46:47], 0x140000
	s_nop 0
	s_nop 0
	v_pk_mul_f32 v[46:47], v[46:47], v[52:53] op_sel_hi:[1,0]
	v_pk_mul_f32 v[54:55], v[44:45], v[52:53] op_sel_hi:[1,0]
	v_pk_mul_f32 v[44:45], v[42:43], v[52:53] op_sel_hi:[1,0]
	v_cvt_pk_bf16_f32 v42, v46, v47
	v_add_co_u32_e32 v46, vcc, s1, v142
	v_pk_mul_f32 v[48:49], v[48:49], v[52:53] op_sel_hi:[1,0]
	s_nop 0
	v_addc_co_u32_e32 v47, vcc, 0, v143, vcc
	v_cvt_pk_bf16_f32 v43, v48, v49
	v_cvt_pk_bf16_f32 v44, v44, v45
	v_cvt_pk_bf16_f32 v45, v54, v55
	global_store_dwordx4 v[46:47], v[42:45], off
	v_pk_mul_f32 v[40:41], v[40:41], v[52:53] op_sel_hi:[1,0]
	v_pk_mul_f32 v[38:39], v[38:39], v[52:53] op_sel_hi:[1,0]
	v_pk_mul_f32 v[42:43], v[36:37], v[52:53] op_sel_hi:[1,0]
	v_pk_mul_f32 v[36:37], v[34:35], v[52:53] op_sel_hi:[1,0]
	v_cvt_pk_bf16_f32 v34, v38, v39
	v_cvt_pk_bf16_f32 v35, v40, v41
	s_mov_b32 s1, 0x140000
	v_cvt_pk_bf16_f32 v36, v36, v37
	v_cvt_pk_bf16_f32 v37, v42, v43
	global_store_dwordx4 v[50:51], v[34:37], off offset:256
	s_nop 1
	v_mov_b32_e32 v36, v247
	v_lshl_add_u64 v[34:35], v[142:143], 0, s[46:47]
	s_mov_b64 s[46:47], 0x160000
	s_nop 0
	s_nop 0
	v_pk_mul_f32 v[30:31], v[30:31], v[36:37] op_sel_hi:[1,0]
	v_pk_mul_f32 v[38:39], v[28:29], v[36:37] op_sel_hi:[1,0]
	v_pk_mul_f32 v[28:29], v[26:27], v[36:37] op_sel_hi:[1,0]
	v_cvt_pk_bf16_f32 v26, v30, v31
	v_add_co_u32_e32 v30, vcc, s1, v142
	v_pk_mul_f32 v[32:33], v[32:33], v[36:37] op_sel_hi:[1,0]
	s_nop 0
	v_addc_co_u32_e32 v31, vcc, 0, v143, vcc
	v_cvt_pk_bf16_f32 v27, v32, v33
	v_cvt_pk_bf16_f32 v28, v28, v29
	v_cvt_pk_bf16_f32 v29, v38, v39
	global_store_dwordx4 v[30:31], v[26:29], off
	v_pk_mul_f32 v[24:25], v[24:25], v[36:37] op_sel_hi:[1,0]
	v_pk_mul_f32 v[22:23], v[22:23], v[36:37] op_sel_hi:[1,0]
	v_pk_mul_f32 v[26:27], v[20:21], v[36:37] op_sel_hi:[1,0]
	v_pk_mul_f32 v[20:21], v[18:19], v[36:37] op_sel_hi:[1,0]
	v_cvt_pk_bf16_f32 v18, v22, v23
	v_cvt_pk_bf16_f32 v19, v24, v25
	s_mov_b32 s1, 0x160000
	v_cvt_pk_bf16_f32 v20, v20, v21
	v_cvt_pk_bf16_f32 v21, v26, v27
	global_store_dwordx4 v[34:35], v[18:21], off offset:256
	s_nop 1
	v_mov_b32_e32 v20, v248
	v_lshl_add_u64 v[18:19], v[142:143], 0, s[46:47]
	s_mov_b64 s[46:47], s[42:43]
	s_nop 0
	s_nop 0
	v_pk_mul_f32 v[14:15], v[14:15], v[20:21] op_sel_hi:[1,0]
	v_pk_mul_f32 v[22:23], v[12:13], v[20:21] op_sel_hi:[1,0]
	v_pk_mul_f32 v[12:13], v[10:11], v[20:21] op_sel_hi:[1,0]
	v_cvt_pk_bf16_f32 v10, v14, v15
	v_add_co_u32_e32 v14, vcc, s1, v142
	v_pk_mul_f32 v[16:17], v[16:17], v[20:21] op_sel_hi:[1,0]
	s_nop 0
	v_addc_co_u32_e32 v15, vcc, 0, v143, vcc
	v_cvt_pk_bf16_f32 v11, v16, v17
	v_cvt_pk_bf16_f32 v12, v12, v13
	v_cvt_pk_bf16_f32 v13, v22, v23
	global_store_dwordx4 v[14:15], v[10:13], off
	s_and_b64 vcc, exec, s[40:41]
	v_pk_mul_f32 v[8:9], v[8:9], v[20:21] op_sel_hi:[1,0]
	v_pk_mul_f32 v[10:11], v[4:5], v[20:21] op_sel_hi:[1,0]
	v_pk_mul_f32 v[4:5], v[2:3], v[20:21] op_sel_hi:[1,0]
	v_pk_mul_f32 v[6:7], v[6:7], v[20:21] op_sel_hi:[1,0]
	s_nop 0
	v_cvt_pk_bf16_f32 v2, v6, v7
	v_cvt_pk_bf16_f32 v3, v8, v9
	v_cvt_pk_bf16_f32 v4, v4, v5
	v_cvt_pk_bf16_f32 v5, v10, v11
	global_store_dwordx4 v[18:19], v[2:5], off offset:256
	s_cbranch_vccz .LBB0_498
	s_waitcnt vmcnt(0)
	v_readlane_b32 s84, v254, 44
	s_cmpk_gt_u32 s2, 0xff
	v_readlane_b32 s85, v254, 45
	s_cbranch_scc1 .LBB0_509
	s_barrier
